# nt loads for read-once Y / residual rows in P9 (both variants) and P6 layer 1
# speedup vs baseline: 1.0196x; 1.0039x over previous
; #define GAS __attribute__((address_space(1)))
; __device__ __forceinline__ void unpack8(v4u w, float (&f)[8]) { f[0] = bflo(w.x); f[1] = bfhi(w.x); f[2] = bflo(w.y); f[3] = bfhi(w.y); f[4] = bflo(w.z); f[5] = bfhi(w.z); f[6] = bflo(w.w); f[7] = bfhi(w.w); }
; template <bool XF32, bool FINAL, bool QUANT = false> ...
;     v4u yraw[8]; f32x4 xf[8][2]; v4u xr[8]; float s = 0.f; float am = 0.f;
; #pragma unroll
;     for (int j = 0; j < 8; ++j) yraw[j] = *(const GAS v4u*)(yrow + 8 * lane + 512 * j);
; #pragma unroll
;     for (int j = 0; j < 8; ++j) {
;         if (XF32) { xf[j][0] = *(const GAS f32x4*)((const float*)xrow + 8 * lane + 512 * j); xf[j][1] = *(const GAS f32x4*)((const float*)xrow + 8 * lane + 512 * j + 4); }
;         else xr[j] = *(const GAS v4u*)((const bf16*)xrow + 8 * lane + 512 * j); }
; #pragma unroll
;     for (int j = 0; j < 8; ++j) { float yf[8]; unpack8(yraw[j], yf);
; #pragma unroll
;         for (int e = 0; e < 8; ++e) s += yf[e] * yf[e]; }
;     const float rstd = 1.0f / sqrtf(wave_sum(s, lane) * (1.0f / DM) + eps_y);
.LBB0_635:
	v_lshl_add_u64 v[2:3], s[38:39], 0, v[76:77]
	v_add_co_u32_e32 v4, vcc, 0x3d200000, v2
	s_add_u32 s34, s38, s10
	s_nop 0
	v_addc_co_u32_e32 v5, vcc, 0, v3, vcc
	global_load_dwordx4 v[84:87], v[4:5], off nt
	global_load_dwordx4 v[92:95], v[4:5], off offset:1024 nt
	global_load_dwordx4 v[100:103], v[4:5], off offset:2048 nt
	global_load_dwordx4 v[54:57], v[4:5], off offset:3072 nt
	v_add_co_u32_e32 v6, vcc, s52, v2
	s_addc_u32 s35, s39, s11
	s_nop 0
	v_addc_co_u32_e32 v7, vcc, 0, v3, vcc
	global_load_dwordx4 v[18:21], v[6:7], off offset:3072 nt
	global_load_dwordx4 v[22:25], v[6:7], off nt
	global_load_dwordx4 v[26:29], v[62:63], off offset:16
	global_load_dwordx4 v[34:37], v[62:63], off
	global_load_dwordx4 v[30:33], v[62:63], off offset:2064
	global_load_dwordx4 v[38:41], v[62:63], off offset:2048
	global_load_dwordx4 v[50:53], v[6:7], off offset:2048 nt
	global_load_dwordx4 v[58:61], v[6:7], off offset:1024 nt
	v_add_co_u32_e32 v82, vcc, s46, v2
	s_waitcnt vmcnt(11)
	v_and_b32_e32 v150, 0xffff0000, v84
	v_lshlrev_b32_e32 v151, 16, v85
	v_lshlrev_b32_e32 v126, 16, v84
	v_and_b32_e32 v127, 0xffff0000, v85
	s_waitcnt vmcnt(8)
	v_and_b32_e32 v104, 0xffff0000, v54
	v_lshlrev_b32_e32 v105, 16, v55
	v_lshlrev_b32_e32 v108, 16, v54
	v_and_b32_e32 v109, 0xffff0000, v55
	s_waitcnt vmcnt(7)
	v_lshlrev_b32_e32 v130, 16, v20
	v_and_b32_e32 v132, 0xffff0000, v20
	v_and_b32_e32 v134, 0xffff0000, v21
	v_lshlrev_b32_e32 v135, 16, v21
	v_pk_mul_f32 v[20:21], v[126:127], v[126:127]
	v_pk_mul_f32 v[54:55], v[150:151], v[150:151]
	v_lshlrev_b32_e32 v128, 16, v86
	v_add_f32_e32 v1, v20, v54
	v_and_b32_e32 v129, 0xffff0000, v87
	v_add_f32_e32 v1, v55, v1
	v_and_b32_e32 v152, 0xffff0000, v86
	v_lshlrev_b32_e32 v153, 16, v87
	v_pk_mul_f32 v[160:161], v[128:129], v[128:129]
	v_add_f32_e32 v1, v21, v1
	v_pk_mul_f32 v[162:163], v[152:153], v[152:153]
	v_add_f32_e32 v1, v160, v1
	v_add_f32_e32 v1, v162, v1
	v_and_b32_e32 v88, 0xffff0000, v92
	v_lshlrev_b32_e32 v89, 16, v93
	v_lshlrev_b32_e32 v92, 16, v92
	v_and_b32_e32 v93, 0xffff0000, v93
	v_add_f32_e32 v1, v163, v1
	v_pk_mul_f32 v[164:165], v[92:93], v[92:93]
	v_add_f32_e32 v1, v161, v1
	v_pk_mul_f32 v[166:167], v[88:89], v[88:89]
	v_add_f32_e32 v1, v164, v1
	v_add_f32_e32 v1, v166, v1
	v_and_b32_e32 v90, 0xffff0000, v94
	v_lshlrev_b32_e32 v91, 16, v95
	v_lshlrev_b32_e32 v94, 16, v94
	v_and_b32_e32 v95, 0xffff0000, v95
	v_add_f32_e32 v1, v167, v1
	v_pk_mul_f32 v[168:169], v[94:95], v[94:95]
	v_add_f32_e32 v1, v165, v1
	v_pk_mul_f32 v[170:171], v[90:91], v[90:91]
	v_add_f32_e32 v1, v168, v1
	v_add_f32_e32 v1, v170, v1
	v_and_b32_e32 v96, 0xffff0000, v100
	v_lshlrev_b32_e32 v97, 16, v101
	v_lshlrev_b32_e32 v100, 16, v100
	v_and_b32_e32 v101, 0xffff0000, v101
	v_add_f32_e32 v1, v171, v1
	v_pk_mul_f32 v[172:173], v[100:101], v[100:101]
	v_add_f32_e32 v1, v169, v1
	v_pk_mul_f32 v[174:175], v[96:97], v[96:97]
	v_add_f32_e32 v1, v172, v1
	v_add_f32_e32 v1, v174, v1
	v_and_b32_e32 v98, 0xffff0000, v102
	v_lshlrev_b32_e32 v99, 16, v103
	v_lshlrev_b32_e32 v102, 16, v102
	v_and_b32_e32 v103, 0xffff0000, v103
	v_add_f32_e32 v1, v175, v1
	v_pk_mul_f32 v[176:177], v[102:103], v[102:103]
	v_add_f32_e32 v1, v173, v1
	v_pk_mul_f32 v[178:179], v[98:99], v[98:99]
	v_add_f32_e32 v1, v176, v1
	v_add_f32_e32 v1, v178, v1
	v_add_f32_e32 v1, v179, v1
	v_pk_mul_f32 v[182:183], v[108:109], v[108:109]
	v_add_f32_e32 v1, v177, v1
	v_pk_mul_f32 v[184:185], v[104:105], v[104:105]
	v_add_f32_e32 v1, v182, v1
	v_add_f32_e32 v1, v184, v1
	v_lshlrev_b32_e32 v110, 16, v56
	v_and_b32_e32 v111, 0xffff0000, v57
	v_add_f32_e32 v1, v185, v1
	v_and_b32_e32 v106, 0xffff0000, v56
	v_lshlrev_b32_e32 v107, 16, v57
	v_pk_mul_f32 v[56:57], v[110:111], v[110:111]
	v_add_f32_e32 v1, v183, v1
	v_pk_mul_f32 v[196:197], v[106:107], v[106:107]
	v_add_f32_e32 v1, v56, v1
	v_add_f32_e32 v1, v196, v1
	s_waitcnt vmcnt(6)
	v_lshlrev_b32_e32 v112, 16, v22
	v_and_b32_e32 v113, 0xffff0000, v23
	v_add_f32_e32 v1, v197, v1
	v_and_b32_e32 v116, 0xffff0000, v22
	v_lshlrev_b32_e32 v117, 16, v23
	v_pk_mul_f32 v[22:23], v[112:113], v[112:113]
	v_add_f32_e32 v1, v57, v1
	v_pk_mul_f32 v[198:199], v[116:117], v[116:117]
	v_add_f32_e32 v1, v22, v1
	v_add_f32_e32 v1, v198, v1
	v_lshlrev_b32_e32 v118, 16, v24
	v_and_b32_e32 v119, 0xffff0000, v25
	v_add_f32_e32 v1, v199, v1
	v_and_b32_e32 v120, 0xffff0000, v24
	v_lshlrev_b32_e32 v121, 16, v25
	v_pk_mul_f32 v[24:25], v[118:119], v[118:119]
	v_add_f32_e32 v1, v23, v1
	v_pk_mul_f32 v[200:201], v[120:121], v[120:121]
	v_add_f32_e32 v1, v24, v1
	v_add_f32_e32 v1, v200, v1
	s_waitcnt vmcnt(0)
; #define GAS __attribute__((address_space(1)))
; __device__ __forceinline__ void unpack8(v4u w, float (&f)[8]) { f[0] = bflo(w.x); f[1] = bfhi(w.x); f[2] = bflo(w.y); f[3] = bfhi(w.y); f[4] = bflo(w.z); f[5] = bfhi(w.z); f[6] = bflo(w.w); f[7] = bfhi(w.w); }
; template <bool XF32, bool FINAL, bool QUANT = false> ...
;     v4u yraw[8]; f32x4 xf[8][2]; v4u xr[8]; float s = 0.f; float am = 0.f;
; #pragma unroll
;     for (int j = 0; j < 8; ++j) yraw[j] = *(const GAS v4u*)(yrow + 8 * lane + 512 * j);
; #pragma unroll
;     for (int j = 0; j < 8; ++j) {
;         if (XF32) { xf[j][0] = *(const GAS f32x4*)((const float*)xrow + 8 * lane + 512 * j); xf[j][1] = *(const GAS f32x4*)((const float*)xrow + 8 * lane + 512 * j + 4); }
;         else xr[j] = *(const GAS v4u*)((const bf16*)xrow + 8 * lane + 512 * j); }
; #pragma unroll
;     for (int j = 0; j < 8; ++j) { float yf[8]; unpack8(yraw[j], yf);
; #pragma unroll
;         for (int e = 0; e < 8; ++e) s += yf[e] * yf[e]; }
;     const float rstd = 1.0f / sqrtf(wave_sum(s, lane) * (1.0f / DM) + eps_y);
;     float s2 = 0.f;
; #pragma unroll
;     for (int j = 0; j < 8; ++j) { const int c = 8 * lane + 512 * j; float yf[8], x[8]; unpack8(yraw[j], yf);
;         if (XF32) { x[0] = xf[j][0].x; x[1] = xf[j][0].y; x[2] = xf[j][0].z; x[3] = xf[j][0].w; x[4] = xf[j][1].x; x[5] = xf[j][1].y; x[6] = xf[j][1].z; x[7] = xf[j][1].w; }
;         else unpack8(xr[j], x);
;         const f32x4 g0 = *(const GAS f32x4*)(gpost + c), g1 = *(const GAS f32x4*)(gpost + c + 4);
; #pragma unroll
;         for (int e = 0; e < 4; ++e) { x[e] += yf[e] * rstd * g0[e]; x[4 + e] += yf[4 + e] * rstd * g1[e]; }
	v_lshlrev_b32_e32 v84, 16, v58
	v_and_b32_e32 v85, 0xffff0000, v59
	v_add_f32_e32 v1, v201, v1
	v_and_b32_e32 v86, 0xffff0000, v58
	v_lshlrev_b32_e32 v87, 16, v59
	v_pk_mul_f32 v[58:59], v[84:85], v[84:85]
	v_add_f32_e32 v1, v25, v1
	v_pk_mul_f32 v[214:215], v[86:87], v[86:87]
	v_add_f32_e32 v1, v58, v1
	v_add_f32_e32 v1, v214, v1
	v_lshlrev_b32_e32 v122, 16, v60
	v_and_b32_e32 v123, 0xffff0000, v61
	v_add_f32_e32 v1, v215, v1
	v_and_b32_e32 v124, 0xffff0000, v60
	v_lshlrev_b32_e32 v125, 16, v61
	v_pk_mul_f32 v[60:61], v[122:123], v[122:123]
	v_add_f32_e32 v1, v59, v1
	v_pk_mul_f32 v[216:217], v[124:125], v[124:125]
	v_add_f32_e32 v1, v60, v1
	v_add_f32_e32 v1, v216, v1
	v_lshlrev_b32_e32 v138, 16, v50
	v_and_b32_e32 v139, 0xffff0000, v51
	v_add_f32_e32 v1, v217, v1
	v_and_b32_e32 v136, 0xffff0000, v50
	v_lshlrev_b32_e32 v137, 16, v51
	v_pk_mul_f32 v[50:51], v[138:139], v[138:139]
	v_add_f32_e32 v1, v61, v1
	v_pk_mul_f32 v[218:219], v[136:137], v[136:137]
	v_add_f32_e32 v1, v50, v1
	v_add_f32_e32 v1, v218, v1
	v_addc_co_u32_e32 v83, vcc, 0, v3, vcc
	v_lshlrev_b32_e32 v142, 16, v52
	v_and_b32_e32 v143, 0xffff0000, v53
	v_add_f32_e32 v1, v219, v1
	v_add_co_u32_e32 v80, vcc, s47, v2
	v_and_b32_e32 v140, 0xffff0000, v52
	v_lshlrev_b32_e32 v141, 16, v53
	v_pk_mul_f32 v[52:53], v[142:143], v[142:143]
	v_add_f32_e32 v1, v51, v1
	v_addc_co_u32_e32 v81, vcc, 0, v3, vcc
	global_load_dwordx4 v[42:45], v[82:83], off offset:1024 nt
	global_load_dwordx4 v[14:17], v[82:83], off offset:2048 nt
	global_load_dwordx4 v[46:49], v[80:81], off offset:-4096 nt
	global_load_dwordx4 v[10:13], v[82:83], off offset:3072 nt
	global_load_dwordx4 v[6:9], v[80:81], off nt
	global_load_dwordx4 v[2:5], v[80:81], off offset:1024 nt
	v_pk_mul_f32 v[220:221], v[140:141], v[140:141]
	v_add_f32_e32 v1, v52, v1
	v_add_f32_e32 v1, v220, v1
	v_lshlrev_b32_e32 v146, 16, v18
	v_and_b32_e32 v147, 0xffff0000, v19
	v_add_f32_e32 v1, v221, v1
	v_and_b32_e32 v144, 0xffff0000, v18
	v_lshlrev_b32_e32 v145, 16, v19
	v_pk_mul_f32 v[18:19], v[146:147], v[146:147]
	v_add_f32_e32 v1, v53, v1
	v_pk_mul_f32 v[222:223], v[144:145], v[144:145]
	v_add_f32_e32 v1, v18, v1
	v_add_f32_e32 v1, v222, v1
	v_add_f32_e32 v1, v223, v1
	v_add_f32_e32 v1, v19, v1
	v_fmac_f32_e32 v1, v130, v130
	v_pk_mul_f32 v[194:195], v[134:135], v[134:135]
	v_fmac_f32_e32 v1, v132, v132
	v_add_f32_e32 v1, v195, v1
	v_add_f32_e32 v1, v194, v1
	ds_bpermute_b32 v52, v154, v1
	v_mov_b32_e32 v57, v28
	v_mov_b32_e32 v56, v27
	v_mov_b32_e32 v27, v29
	v_mov_b32_e32 v163, v40
	s_waitcnt lgkmcnt(0)
	v_add_f32_e32 v1, v1, v52
	ds_bpermute_b32 v54, v155, v1
	v_mov_b32_e32 v169, v32
	v_mov_b32_e32 v168, v31
	v_mov_b32_e32 v31, v33
	v_mov_b32_e32 v52, v35
	s_waitcnt lgkmcnt(0)
	v_add_f32_e32 v1, v1, v54
	ds_bpermute_b32 v54, v156, v1
	v_mov_b32_e32 v53, v36
	v_mov_b32_e32 v35, v37
	v_mov_b32_e32 v162, v39
	v_mov_b32_e32 v39, v41
	s_waitcnt lgkmcnt(0)
	v_add_f32_e32 v1, v1, v54
	ds_bpermute_b32 v54, v157, v1
	global_load_dwordx4 v[22:25], v[80:81], off offset:2048 nt
	global_load_dwordx4 v[18:21], v[80:81], off offset:3072 nt
	v_mov_b32_e32 v133, v135
	v_mov_b32_e32 v131, v134
	s_waitcnt lgkmcnt(0)
	v_add_f32_e32 v1, v1, v54
	ds_bpermute_b32 v28, v158, v1
	s_waitcnt lgkmcnt(0)
	v_add_f32_e32 v1, v1, v28
	ds_bpermute_b32 v28, v159, v1
	s_waitcnt lgkmcnt(0)
	v_add_f32_e32 v1, v1, v28
	v_fmamk_f32 v1, v1, 0x39800000, v204
	v_mul_f32_e32 v28, 0x4f800000, v1
	v_cmp_gt_f32_e32 vcc, s73, v1
	s_waitcnt vmcnt(7)
	v_lshlrev_b32_e32 v165, 16, v45
	v_cndmask_b32_e32 v1, v1, v28, vcc
	v_sqrt_f32_e32 v28, v1
	s_waitcnt vmcnt(5)
	v_and_b32_e32 v50, 0xffff0000, v46
	v_lshlrev_b32_e32 v51, 16, v47
	v_and_b32_e32 v36, 0xffff0000, v48
	v_add_u32_e32 v29, -1, v28
	v_fma_f32 v40, -v29, v28, v1
	v_cmp_ge_f32_e64 s[44:45], 0, v40
	v_add_u32_e32 v40, 1, v28
	v_lshlrev_b32_e32 v37, 16, v49
	v_cndmask_b32_e64 v29, v28, v29, s[44:45]
	v_fma_f32 v28, -v40, v28, v1
	v_cmp_lt_f32_e64 s[44:45], 0, v28
	v_lshlrev_b32_e32 v46, 16, v46
	v_and_b32_e32 v47, 0xffff0000, v47
	v_cndmask_b32_e64 v28, v29, v40, s[44:45]
	v_mul_f32_e32 v29, 0x37800000, v28
	v_cndmask_b32_e32 v28, v28, v29, vcc
	v_cmp_class_f32_e32 vcc, v1, v205
	v_lshlrev_b32_e32 v48, 16, v48
	v_and_b32_e32 v49, 0xffff0000, v49
	v_cndmask_b32_e32 v1, v28, v1, vcc
	v_div_scale_f32 v28, s[12:13], v1, v1, 1.0
	v_rcp_f32_e32 v29, v28
	v_and_b32_e32 v167, 0xffff0000, v45
	v_and_b32_e32 v160, 0xffff0000, v42
	v_lshlrev_b32_e32 v161, 16, v43
	v_fma_f32 v32, -v28, v29, 1.0
	v_fmac_f32_e32 v29, v32, v29
	v_div_scale_f32 v32, vcc, 1.0, v1, 1.0
	v_mul_f32_e32 v33, v32, v29
	v_fma_f32 v40, -v28, v33, v32
	v_fmac_f32_e32 v33, v40, v29
	v_fma_f32 v28, -v28, v33, v32
	v_div_fmas_f32 v28, v28, v29, v33
	v_div_fixup_f32 v148, v28, v1, 1.0
	v_pk_mul_f32 v[28:29], v[148:149], v[150:151] op_sel_hi:[0,1]
	v_pk_fma_f32 v[54:55], v[52:53], v[28:29], v[50:51]
	v_pk_mul_f32 v[28:29], v[148:149], v[152:153] op_sel_hi:[0,1]
	v_pk_fma_f32 v[56:57], v[56:57], v[28:29], v[36:37]
	v_pk_mul_f32 v[28:29], v[148:149], v[126:127] op_sel_hi:[0,1]
	v_pk_fma_f32 v[58:59], v[34:35], v[28:29], v[46:47]
	v_pk_mul_f32 v[28:29], v[148:149], v[128:129] op_sel_hi:[0,1]
	v_pk_fma_f32 v[60:61], v[26:27], v[28:29], v[48:49]
	v_and_b32_sdwa v1, v55, v203 dst_sel:DWORD dst_unused:UNUSED_PAD src0_sel:WORD_1 src1_sel:DWORD
	v_and_b32_sdwa v26, v54, v203 dst_sel:DWORD dst_unused:UNUSED_PAD src0_sel:WORD_1 src1_sel:DWORD
	v_add3_u32 v45, v55, v1, s14
	v_add3_u32 v1, v54, v26, s14
	v_and_b32_e32 v40, 0xffff0000, v1
	v_and_b32_sdwa v1, v59, v203 dst_sel:DWORD dst_unused:UNUSED_PAD src0_sel:WORD_1 src1_sel:DWORD
	v_and_b32_sdwa v26, v58, v203 dst_sel:DWORD dst_unused:UNUSED_PAD src0_sel:WORD_1 src1_sel:DWORD
; #define GAS __attribute__((address_space(1)))
; __device__ __forceinline__ void unpack8(v4u w, float (&f)[8]) { f[0] = bflo(w.x); f[1] = bfhi(w.x); f[2] = bflo(w.y); f[3] = bfhi(w.y); f[4] = bflo(w.z); f[5] = bfhi(w.z); f[6] = bflo(w.w); f[7] = bfhi(w.w); }
; __device__ __forceinline__ v4u pack8(const float (&o)[8]) { v4u w; w.x = pk2(o[0], o[1]); w.y = pk2(o[2], o[3]); w.z = pk2(o[4], o[5]); w.w = pk2(o[6], o[7]); return w; }
; template <bool XF32, bool FINAL, bool QUANT = false> ...
;     ...
;     for (int j = 0; j < 8; ++j) { const int c = 8 * lane + 512 * j; float yf[8], x[8]; unpack8(yraw[j], yf);
;         if (XF32) { x[0] = xf[j][0].x; x[1] = xf[j][0].y; x[2] = xf[j][0].z; x[3] = xf[j][0].w; x[4] = xf[j][1].x; x[5] = xf[j][1].y; x[6] = xf[j][1].z; x[7] = xf[j][1].w; }
;         else unpack8(xr[j], x);
;         const f32x4 g0 = *(const GAS f32x4*)(gpost + c), g1 = *(const GAS f32x4*)(gpost + c + 4);
; #pragma unroll
;         for (int e = 0; e < 4; ++e) { x[e] += yf[e] * rstd * g0[e]; x[4 + e] += yf[4 + e] * rstd * g1[e]; }
;         if (FINAL) { *(GAS f32x4*)(orow + c) = (f32x4){x[0], x[1], x[2], x[3]}; *(GAS f32x4*)(orow + c + 4) = (f32x4){x[4], x[5], x[6], x[7]}; }
;         else {
; #pragma unroll
;             for (int e = 0; e < 8; ++e) s2 += x[e] * x[e];
;             const v4u pw = pack8(x); *(GAS v4u*)(xbrow + c) = pw;
	v_add3_u32 v1, v59, v1, s14
	v_add3_u32 v46, v58, v26, s14
	v_and_b32_e32 v37, 0xffff0000, v1
	v_and_b32_sdwa v1, v57, v203 dst_sel:DWORD dst_unused:UNUSED_PAD src0_sel:WORD_1 src1_sel:DWORD
	v_and_b32_sdwa v26, v56, v203 dst_sel:DWORD dst_unused:UNUSED_PAD src0_sel:WORD_1 src1_sel:DWORD
	v_add3_u32 v47, v57, v1, s14
	v_add3_u32 v1, v56, v26, s14
	v_and_b32_sdwa v26, v60, v203 dst_sel:DWORD dst_unused:UNUSED_PAD src0_sel:WORD_1 src1_sel:DWORD
	v_add3_u32 v48, v60, v26, s14
	v_pk_mul_f32 v[26:27], v[148:149], v[88:89] op_sel_hi:[0,1]
	v_and_b32_e32 v164, 0xffff0000, v44
	v_pk_fma_f32 v[88:89], v[162:163], v[26:27], v[160:161]
	v_pk_mul_f32 v[26:27], v[148:149], v[90:91] op_sel_hi:[0,1]
	v_lshlrev_b32_e32 v42, 16, v42
	v_and_b32_e32 v43, 0xffff0000, v43
	v_and_b32_e32 v32, 0xffff0000, v1
	v_and_b32_sdwa v1, v61, v203 dst_sel:DWORD dst_unused:UNUSED_PAD src0_sel:WORD_1 src1_sel:DWORD
	v_pk_fma_f32 v[90:91], v[168:169], v[26:27], v[164:165]
	v_pk_mul_f32 v[26:27], v[148:149], v[92:93] op_sel_hi:[0,1]
	v_lshlrev_b32_e32 v166, 16, v44
	v_add3_u32 v1, v61, v1, s14
	v_pk_fma_f32 v[92:93], v[38:39], v[26:27], v[42:43]
	v_pk_mul_f32 v[26:27], v[148:149], v[94:95] op_sel_hi:[0,1]
	v_and_b32_e32 v29, 0xffff0000, v1
	v_pk_fma_f32 v[94:95], v[30:31], v[26:27], v[166:167]
	v_and_b32_sdwa v1, v89, v203 dst_sel:DWORD dst_unused:UNUSED_PAD src0_sel:WORD_1 src1_sel:DWORD
	v_and_b32_sdwa v26, v88, v203 dst_sel:DWORD dst_unused:UNUSED_PAD src0_sel:WORD_1 src1_sel:DWORD
	v_add3_u32 v31, v89, v1, s14
	v_add3_u32 v1, v88, v26, s14
	v_and_b32_e32 v28, 0xffff0000, v1
	v_and_b32_sdwa v1, v93, v203 dst_sel:DWORD dst_unused:UNUSED_PAD src0_sel:WORD_1 src1_sel:DWORD
	v_and_b32_sdwa v26, v92, v203 dst_sel:DWORD dst_unused:UNUSED_PAD src0_sel:WORD_1 src1_sel:DWORD
	v_add3_u32 v1, v93, v1, s14
	v_add3_u32 v30, v92, v26, s14
	v_and_b32_e32 v27, 0xffff0000, v1
	v_and_b32_sdwa v1, v91, v203 dst_sel:DWORD dst_unused:UNUSED_PAD src0_sel:WORD_1 src1_sel:DWORD
	v_and_b32_sdwa v26, v90, v203 dst_sel:DWORD dst_unused:UNUSED_PAD src0_sel:WORD_1 src1_sel:DWORD
	v_add3_u32 v33, v91, v1, s14
	v_add3_u32 v1, v90, v26, s14
	v_and_b32_e32 v26, 0xffff0000, v1
	v_and_b32_sdwa v1, v95, v203 dst_sel:DWORD dst_unused:UNUSED_PAD src0_sel:WORD_1 src1_sel:DWORD
	v_and_b32_sdwa v34, v94, v203 dst_sel:DWORD dst_unused:UNUSED_PAD src0_sel:WORD_1 src1_sel:DWORD
	v_add3_u32 v1, v95, v1, s14
	v_or_b32_sdwa v51, v37, v45 dst_sel:DWORD dst_unused:UNUSED_PAD src0_sel:DWORD src1_sel:WORD_1
	v_or_b32_sdwa v50, v46, v40 dst_sel:DWORD dst_unused:UNUSED_PAD src0_sel:WORD_1 src1_sel:DWORD
	v_or_b32_sdwa v53, v29, v47 dst_sel:DWORD dst_unused:UNUSED_PAD src0_sel:DWORD src1_sel:WORD_1
	v_or_b32_sdwa v52, v48, v32 dst_sel:DWORD dst_unused:UNUSED_PAD src0_sel:WORD_1 src1_sel:DWORD
	v_add3_u32 v34, v94, v34, s14
	v_and_b32_e32 v1, 0xffff0000, v1
	global_store_dwordx4 v[80:81], v[50:53], off offset:-4096
	v_and_b32_e32 v38, 0xffff0000, v14
	v_lshlrev_b32_e32 v39, 16, v15
	v_or_b32_sdwa v51, v27, v31 dst_sel:DWORD dst_unused:UNUSED_PAD src0_sel:DWORD src1_sel:WORD_1
	v_or_b32_sdwa v50, v30, v28 dst_sel:DWORD dst_unused:UNUSED_PAD src0_sel:WORD_1 src1_sel:DWORD
	v_or_b32_sdwa v53, v1, v33 dst_sel:DWORD dst_unused:UNUSED_PAD src0_sel:DWORD src1_sel:WORD_1
	v_or_b32_sdwa v52, v34, v26 dst_sel:DWORD dst_unused:UNUSED_PAD src0_sel:WORD_1 src1_sel:DWORD
	global_store_dwordx4 v[82:83], v[50:53], off offset:1024
	global_load_dwordx4 v[50:53], v[64:65], off
	global_load_dwordx4 v[126:129], v[64:65], off offset:16
	v_pk_mul_f32 v[96:97], v[148:149], v[96:97] op_sel_hi:[0,1]
	v_and_b32_e32 v42, 0xffff0000, v16
	v_lshlrev_b32_e32 v43, 16, v17
	v_lshlrev_b32_e32 v14, 16, v14
	v_and_b32_e32 v15, 0xffff0000, v15
	v_lshlrev_b32_e32 v16, 16, v16
	v_and_b32_e32 v17, 0xffff0000, v17
	v_pk_mul_f32 v[104:105], v[148:149], v[104:105] op_sel_hi:[0,1]
	v_pk_mul_f32 v[116:117], v[148:149], v[116:117] op_sel_hi:[0,1]
	v_pk_mul_f32 v[120:121], v[148:149], v[120:121] op_sel_hi:[0,1]
	v_pk_mul_f32 v[118:119], v[148:149], v[118:119] op_sel_hi:[0,1]
	v_pk_mul_f32 v[86:87], v[148:149], v[86:87] op_sel_hi:[0,1]
	v_pk_mul_f32 v[162:163], v[148:149], v[124:125] op_sel_hi:[0,1]
	v_pk_mul_f32 v[84:85], v[148:149], v[84:85] op_sel_hi:[0,1]
	v_pk_mul_f32 v[164:165], v[148:149], v[122:123] op_sel_hi:[0,1]
	s_waitcnt vmcnt(5)
	v_and_b32_e32 v134, 0xffff0000, v24
	v_lshlrev_b32_e32 v135, 16, v25
	s_waitcnt vmcnt(4)
	v_lshlrev_b32_e32 v168, 16, v18
	v_and_b32_e32 v169, 0xffff0000, v19
	v_and_b32_e32 v170, 0xffff0000, v20
	v_lshlrev_b32_e32 v171, 16, v21
	v_lshlrev_b32_e32 v172, 16, v20
	v_and_b32_e32 v173, 0xffff0000, v21
	v_pk_mul_f32 v[20:21], v[148:149], v[140:141] op_sel_hi:[0,1]
	v_pk_mul_f32 v[176:177], v[148:149], v[132:133] op_sel_hi:[0,1]
	v_pk_mul_f32 v[178:179], v[148:149], v[130:131] op_sel_hi:[0,1]
	v_pk_mul_f32 v[174:175], v[148:149], v[144:145] op_sel_hi:[0,1]
	v_pk_mul_f32 v[182:183], v[58:59], v[58:59]
	v_pk_mul_f32 v[184:185], v[54:55], v[54:55]
	v_pk_mul_f32 v[194:195], v[60:61], v[60:61]
	v_pk_mul_f32 v[196:197], v[56:57], v[56:57]
	v_pk_mul_f32 v[146:147], v[148:149], v[146:147] op_sel_hi:[0,1]
	s_waitcnt vmcnt(1)
	v_mov_b32_e32 v150, v51
	v_mov_b32_e32 v151, v52
	v_pk_fma_f32 v[96:97], v[150:151], v[96:97], v[38:39]
	v_pk_mul_f32 v[38:39], v[148:149], v[98:99] op_sel_hi:[0,1]
	s_waitcnt vmcnt(0)
; #define GAS __attribute__((address_space(1)))
; __device__ __forceinline__ void unpack8(v4u w, float (&f)[8]) { f[0] = bflo(w.x); f[1] = bfhi(w.x); f[2] = bflo(w.y); f[3] = bfhi(w.y); f[4] = bflo(w.z); f[5] = bfhi(w.z); f[6] = bflo(w.w); f[7] = bfhi(w.w); }
; __device__ __forceinline__ v4u pack8(const float (&o)[8]) { v4u w; w.x = pk2(o[0], o[1]); w.y = pk2(o[2], o[3]); w.z = pk2(o[4], o[5]); w.w = pk2(o[6], o[7]); return w; }
; template <bool XF32, bool FINAL, bool QUANT = false> ...
;     ...
;     for (int j = 0; j < 8; ++j) { const int c = 8 * lane + 512 * j; float yf[8], x[8]; unpack8(yraw[j], yf);
;         if (XF32) { x[0] = xf[j][0].x; x[1] = xf[j][0].y; x[2] = xf[j][0].z; x[3] = xf[j][0].w; x[4] = xf[j][1].x; x[5] = xf[j][1].y; x[6] = xf[j][1].z; x[7] = xf[j][1].w; }
;         else unpack8(xr[j], x);
;         const f32x4 g0 = *(const GAS f32x4*)(gpost + c), g1 = *(const GAS f32x4*)(gpost + c + 4);
; #pragma unroll
;         for (int e = 0; e < 4; ++e) { x[e] += yf[e] * rstd * g0[e]; x[4 + e] += yf[4 + e] * rstd * g1[e]; }
;         if (FINAL) { *(GAS f32x4*)(orow + c) = (f32x4){x[0], x[1], x[2], x[3]}; *(GAS f32x4*)(orow + c + 4) = (f32x4){x[4], x[5], x[6], x[7]}; }
;         else {
; #pragma unroll
;             for (int e = 0; e < 8; ++e) s2 += x[e] * x[e];
;             const v4u pw = pack8(x); *(GAS v4u*)(xbrow + c) = pw;
	v_mov_b32_e32 v98, v127
	v_mov_b32_e32 v99, v128
	v_pk_fma_f32 v[98:99], v[98:99], v[38:39], v[42:43]
	v_pk_mul_f32 v[38:39], v[148:149], v[100:101] op_sel_hi:[0,1]
	v_mov_b32_e32 v51, v53
	v_pk_fma_f32 v[100:101], v[50:51], v[38:39], v[14:15]
	v_pk_mul_f32 v[14:15], v[148:149], v[102:103] op_sel_hi:[0,1]
	v_mov_b32_e32 v127, v129
	v_pk_fma_f32 v[102:103], v[126:127], v[14:15], v[16:17]
	v_and_b32_sdwa v14, v97, v203 dst_sel:DWORD dst_unused:UNUSED_PAD src0_sel:WORD_1 src1_sel:DWORD
	v_and_b32_sdwa v15, v96, v203 dst_sel:DWORD dst_unused:UNUSED_PAD src0_sel:WORD_1 src1_sel:DWORD
	v_add3_u32 v35, v97, v14, s14
	v_add3_u32 v14, v96, v15, s14
	v_and_b32_e32 v16, 0xffff0000, v14
	v_and_b32_sdwa v14, v101, v203 dst_sel:DWORD dst_unused:UNUSED_PAD src0_sel:WORD_1 src1_sel:DWORD
	v_and_b32_sdwa v15, v100, v203 dst_sel:DWORD dst_unused:UNUSED_PAD src0_sel:WORD_1 src1_sel:DWORD
	v_add3_u32 v14, v101, v14, s14
	v_add3_u32 v36, v100, v15, s14
	v_and_b32_e32 v17, 0xffff0000, v14
	v_and_b32_sdwa v14, v99, v203 dst_sel:DWORD dst_unused:UNUSED_PAD src0_sel:WORD_1 src1_sel:DWORD
	v_and_b32_sdwa v15, v98, v203 dst_sel:DWORD dst_unused:UNUSED_PAD src0_sel:WORD_1 src1_sel:DWORD
	v_add3_u32 v39, v99, v14, s14
	v_add3_u32 v14, v98, v15, s14
	v_and_b32_sdwa v15, v103, v203 dst_sel:DWORD dst_unused:UNUSED_PAD src0_sel:WORD_1 src1_sel:DWORD
	v_and_b32_sdwa v38, v102, v203 dst_sel:DWORD dst_unused:UNUSED_PAD src0_sel:WORD_1 src1_sel:DWORD
	v_add3_u32 v15, v103, v15, s14
	v_and_b32_e32 v14, 0xffff0000, v14
	v_add3_u32 v38, v102, v38, s14
	v_and_b32_e32 v15, 0xffff0000, v15
	v_or_b32_sdwa v51, v17, v35 dst_sel:DWORD dst_unused:UNUSED_PAD src0_sel:DWORD src1_sel:WORD_1
	v_or_b32_sdwa v50, v36, v16 dst_sel:DWORD dst_unused:UNUSED_PAD src0_sel:WORD_1 src1_sel:DWORD
	v_or_b32_sdwa v53, v15, v39 dst_sel:DWORD dst_unused:UNUSED_PAD src0_sel:DWORD src1_sel:WORD_1
	v_or_b32_sdwa v52, v38, v14 dst_sel:DWORD dst_unused:UNUSED_PAD src0_sel:WORD_1 src1_sel:DWORD
	global_store_dwordx4 v[82:83], v[50:53], off offset:2048
	global_load_dwordx4 v[50:53], v[66:67], off
	s_nop 0
	global_load_dwordx4 v[126:129], v[66:67], off offset:16
	v_and_b32_e32 v42, 0xffff0000, v10
	v_lshlrev_b32_e32 v43, 16, v11
	v_and_b32_e32 v150, 0xffff0000, v12
	v_lshlrev_b32_e32 v151, 16, v13
	v_lshlrev_b32_e32 v10, 16, v10
	v_and_b32_e32 v11, 0xffff0000, v11
	v_lshlrev_b32_e32 v12, 16, v12
	v_and_b32_e32 v13, 0xffff0000, v13
	s_waitcnt vmcnt(1)
	v_mov_b32_e32 v152, v51
	v_mov_b32_e32 v153, v52
	v_pk_fma_f32 v[104:105], v[152:153], v[104:105], v[42:43]
	v_pk_mul_f32 v[42:43], v[148:149], v[106:107] op_sel_hi:[0,1]
	s_waitcnt vmcnt(0)
	v_mov_b32_e32 v106, v127
	v_mov_b32_e32 v107, v128
	v_pk_fma_f32 v[106:107], v[106:107], v[42:43], v[150:151]
	v_pk_mul_f32 v[42:43], v[148:149], v[108:109] op_sel_hi:[0,1]
	v_mov_b32_e32 v51, v53
	v_pk_fma_f32 v[108:109], v[50:51], v[42:43], v[10:11]
	v_pk_mul_f32 v[10:11], v[148:149], v[110:111] op_sel_hi:[0,1]
	v_mov_b32_e32 v127, v129
	v_pk_fma_f32 v[110:111], v[126:127], v[10:11], v[12:13]
	v_and_b32_sdwa v10, v105, v203 dst_sel:DWORD dst_unused:UNUSED_PAD src0_sel:WORD_1 src1_sel:DWORD
	v_and_b32_sdwa v11, v104, v203 dst_sel:DWORD dst_unused:UNUSED_PAD src0_sel:WORD_1 src1_sel:DWORD
	v_add3_u32 v41, v105, v10, s14
	v_add3_u32 v10, v104, v11, s14
	v_and_b32_e32 v12, 0xffff0000, v10
	v_and_b32_sdwa v10, v109, v203 dst_sel:DWORD dst_unused:UNUSED_PAD src0_sel:WORD_1 src1_sel:DWORD
	v_and_b32_sdwa v11, v108, v203 dst_sel:DWORD dst_unused:UNUSED_PAD src0_sel:WORD_1 src1_sel:DWORD
	v_add3_u32 v10, v109, v10, s14
	v_add3_u32 v42, v108, v11, s14
	v_and_b32_e32 v13, 0xffff0000, v10
	v_and_b32_sdwa v10, v107, v203 dst_sel:DWORD dst_unused:UNUSED_PAD src0_sel:WORD_1 src1_sel:DWORD
	v_and_b32_sdwa v11, v106, v203 dst_sel:DWORD dst_unused:UNUSED_PAD src0_sel:WORD_1 src1_sel:DWORD
	v_add3_u32 v43, v107, v10, s14
	v_add3_u32 v10, v106, v11, s14
	v_and_b32_sdwa v11, v111, v203 dst_sel:DWORD dst_unused:UNUSED_PAD src0_sel:WORD_1 src1_sel:DWORD
	v_and_b32_sdwa v44, v110, v203 dst_sel:DWORD dst_unused:UNUSED_PAD src0_sel:WORD_1 src1_sel:DWORD
	v_add3_u32 v11, v111, v11, s14
	v_and_b32_e32 v10, 0xffff0000, v10
	v_add3_u32 v44, v110, v44, s14
	v_and_b32_e32 v11, 0xffff0000, v11
	v_or_b32_sdwa v51, v13, v41 dst_sel:DWORD dst_unused:UNUSED_PAD src0_sel:DWORD src1_sel:WORD_1
	v_or_b32_sdwa v50, v42, v12 dst_sel:DWORD dst_unused:UNUSED_PAD src0_sel:WORD_1 src1_sel:DWORD
	v_or_b32_sdwa v53, v11, v43 dst_sel:DWORD dst_unused:UNUSED_PAD src0_sel:DWORD src1_sel:WORD_1
	v_or_b32_sdwa v52, v44, v10 dst_sel:DWORD dst_unused:UNUSED_PAD src0_sel:WORD_1 src1_sel:DWORD
	global_store_dwordx4 v[82:83], v[50:53], off offset:3072
	global_load_dwordx4 v[50:53], v[68:69], off
	global_load_dwordx4 v[126:129], v[68:69], off offset:16
	v_and_b32_e32 v82, 0xffff0000, v6
	v_lshlrev_b32_e32 v83, 16, v7
	v_lshlrev_b32_e32 v6, 16, v6
	v_and_b32_e32 v7, 0xffff0000, v7
	v_and_b32_e32 v150, 0xffff0000, v8
	v_lshlrev_b32_e32 v151, 16, v9
	v_lshlrev_b32_e32 v8, 16, v8
	v_and_b32_e32 v9, 0xffff0000, v9
	v_pk_mul_f32 v[152:153], v[148:149], v[112:113] op_sel_hi:[0,1]
	s_waitcnt vmcnt(1)
	v_mov_b32_e32 v112, v51
	v_mov_b32_e32 v113, v52
	s_waitcnt vmcnt(0)
; #define GAS __attribute__((address_space(1)))
; __device__ __forceinline__ void unpack8(v4u w, float (&f)[8]) { f[0] = bflo(w.x); f[1] = bfhi(w.x); f[2] = bflo(w.y); f[3] = bfhi(w.y); f[4] = bflo(w.z); f[5] = bfhi(w.z); f[6] = bflo(w.w); f[7] = bfhi(w.w); }
; __device__ __forceinline__ v4u pack8(const float (&o)[8]) { v4u w; w.x = pk2(o[0], o[1]); w.y = pk2(o[2], o[3]); w.z = pk2(o[4], o[5]); w.w = pk2(o[6], o[7]); return w; }
; template <bool XF32, bool FINAL, bool QUANT = false> ...
;     ...
;     for (int j = 0; j < 8; ++j) { const int c = 8 * lane + 512 * j; float yf[8], x[8]; unpack8(yraw[j], yf);
;         if (XF32) { x[0] = xf[j][0].x; x[1] = xf[j][0].y; x[2] = xf[j][0].z; x[3] = xf[j][0].w; x[4] = xf[j][1].x; x[5] = xf[j][1].y; x[6] = xf[j][1].z; x[7] = xf[j][1].w; }
;         else unpack8(xr[j], x);
;         const f32x4 g0 = *(const GAS f32x4*)(gpost + c), g1 = *(const GAS f32x4*)(gpost + c + 4);
; #pragma unroll
;         for (int e = 0; e < 4; ++e) { x[e] += yf[e] * rstd * g0[e]; x[4 + e] += yf[4 + e] * rstd * g1[e]; }
;         if (FINAL) { *(GAS f32x4*)(orow + c) = (f32x4){x[0], x[1], x[2], x[3]}; *(GAS f32x4*)(orow + c + 4) = (f32x4){x[4], x[5], x[6], x[7]}; }
;         else {
; #pragma unroll
;             for (int e = 0; e < 8; ++e) s2 += x[e] * x[e];
;             const v4u pw = pack8(x); *(GAS v4u*)(xbrow + c) = pw;
	v_mov_b32_e32 v160, v127
	v_mov_b32_e32 v161, v128
	v_mov_b32_e32 v51, v53
	v_mov_b32_e32 v127, v129
	v_pk_fma_f32 v[116:117], v[112:113], v[116:117], v[82:83]
	v_pk_fma_f32 v[112:113], v[160:161], v[120:121], v[150:151]
	v_pk_fma_f32 v[120:121], v[50:51], v[152:153], v[6:7]
	v_pk_fma_f32 v[118:119], v[126:127], v[118:119], v[8:9]
	v_and_b32_sdwa v6, v117, v203 dst_sel:DWORD dst_unused:UNUSED_PAD src0_sel:WORD_1 src1_sel:DWORD
	v_and_b32_sdwa v7, v116, v203 dst_sel:DWORD dst_unused:UNUSED_PAD src0_sel:WORD_1 src1_sel:DWORD
	v_and_b32_sdwa v8, v121, v203 dst_sel:DWORD dst_unused:UNUSED_PAD src0_sel:WORD_1 src1_sel:DWORD
	v_and_b32_sdwa v52, v112, v203 dst_sel:DWORD dst_unused:UNUSED_PAD src0_sel:WORD_1 src1_sel:DWORD
	v_and_b32_sdwa v53, v119, v203 dst_sel:DWORD dst_unused:UNUSED_PAD src0_sel:WORD_1 src1_sel:DWORD
	v_and_b32_sdwa v9, v120, v203 dst_sel:DWORD dst_unused:UNUSED_PAD src0_sel:WORD_1 src1_sel:DWORD
	v_and_b32_sdwa v51, v113, v203 dst_sel:DWORD dst_unused:UNUSED_PAD src0_sel:WORD_1 src1_sel:DWORD
	v_and_b32_sdwa v82, v118, v203 dst_sel:DWORD dst_unused:UNUSED_PAD src0_sel:WORD_1 src1_sel:DWORD
	v_add3_u32 v49, v117, v6, s14
	v_add3_u32 v6, v116, v7, s14
	v_add3_u32 v7, v121, v8, s14
	v_add3_u32 v52, v112, v52, s14
	v_add3_u32 v53, v119, v53, s14
	v_add3_u32 v50, v120, v9, s14
	v_add3_u32 v51, v113, v51, s14
	v_and_b32_e32 v8, 0xffff0000, v6
	v_and_b32_e32 v9, 0xffff0000, v7
	v_and_b32_e32 v6, 0xffff0000, v52
	v_add3_u32 v52, v118, v82, s14
	v_and_b32_e32 v7, 0xffff0000, v53
	v_or_b32_sdwa v127, v9, v49 dst_sel:DWORD dst_unused:UNUSED_PAD src0_sel:DWORD src1_sel:WORD_1
	v_or_b32_sdwa v126, v50, v8 dst_sel:DWORD dst_unused:UNUSED_PAD src0_sel:WORD_1 src1_sel:DWORD
	v_or_b32_sdwa v129, v7, v51 dst_sel:DWORD dst_unused:UNUSED_PAD src0_sel:DWORD src1_sel:WORD_1
	v_or_b32_sdwa v128, v52, v6 dst_sel:DWORD dst_unused:UNUSED_PAD src0_sel:WORD_1 src1_sel:DWORD
	global_store_dwordx4 v[80:81], v[126:129], off
	global_load_dwordx4 v[126:129], v[70:71], off
	s_nop 0
	global_load_dwordx4 v[150:153], v[70:71], off offset:16
	v_and_b32_e32 v82, 0xffff0000, v2
	v_lshlrev_b32_e32 v83, 16, v3
	v_lshlrev_b32_e32 v2, 16, v2
	v_and_b32_e32 v3, 0xffff0000, v3
	v_and_b32_e32 v160, 0xffff0000, v4
	v_lshlrev_b32_e32 v161, 16, v5
	v_lshlrev_b32_e32 v4, 16, v4
	v_and_b32_e32 v5, 0xffff0000, v5
	s_waitcnt vmcnt(1)
	v_mov_b32_e32 v122, v127
	v_mov_b32_e32 v123, v128
	s_waitcnt vmcnt(0)
	v_mov_b32_e32 v166, v151
	v_mov_b32_e32 v167, v152
	v_mov_b32_e32 v127, v129
	v_mov_b32_e32 v151, v153
	v_pk_fma_f32 v[124:125], v[122:123], v[86:87], v[82:83]
	v_pk_fma_f32 v[122:123], v[166:167], v[162:163], v[160:161]
	v_pk_fma_f32 v[128:129], v[126:127], v[84:85], v[2:3]
	v_pk_fma_f32 v[126:127], v[150:151], v[164:165], v[4:5]
	v_and_b32_sdwa v2, v125, v203 dst_sel:DWORD dst_unused:UNUSED_PAD src0_sel:WORD_1 src1_sel:DWORD
	v_and_b32_sdwa v3, v124, v203 dst_sel:DWORD dst_unused:UNUSED_PAD src0_sel:WORD_1 src1_sel:DWORD
	v_and_b32_sdwa v4, v129, v203 dst_sel:DWORD dst_unused:UNUSED_PAD src0_sel:WORD_1 src1_sel:DWORD
	v_and_b32_sdwa v5, v128, v203 dst_sel:DWORD dst_unused:UNUSED_PAD src0_sel:WORD_1 src1_sel:DWORD
	v_and_b32_sdwa v82, v122, v203 dst_sel:DWORD dst_unused:UNUSED_PAD src0_sel:WORD_1 src1_sel:DWORD
	v_and_b32_sdwa v86, v127, v203 dst_sel:DWORD dst_unused:UNUSED_PAD src0_sel:WORD_1 src1_sel:DWORD
	v_and_b32_sdwa v53, v123, v203 dst_sel:DWORD dst_unused:UNUSED_PAD src0_sel:WORD_1 src1_sel:DWORD
	v_and_b32_sdwa v87, v126, v203 dst_sel:DWORD dst_unused:UNUSED_PAD src0_sel:WORD_1 src1_sel:DWORD
	v_add3_u32 v83, v125, v2, s14
	v_add3_u32 v2, v124, v3, s14
	v_add3_u32 v3, v129, v4, s14
	v_add3_u32 v84, v128, v5, s14
	v_add3_u32 v4, v122, v82, s14
	v_add3_u32 v5, v127, v86, s14
	v_add3_u32 v85, v123, v53, s14
	v_add3_u32 v86, v126, v87, s14
	v_and_b32_e32 v82, 0xffff0000, v2
	v_and_b32_e32 v53, 0xffff0000, v3
	v_and_b32_e32 v2, 0xffff0000, v4
	v_and_b32_e32 v3, 0xffff0000, v5
	v_or_b32_sdwa v151, v53, v83 dst_sel:DWORD dst_unused:UNUSED_PAD src0_sel:DWORD src1_sel:WORD_1
	v_or_b32_sdwa v150, v84, v82 dst_sel:DWORD dst_unused:UNUSED_PAD src0_sel:WORD_1 src1_sel:DWORD
	v_or_b32_sdwa v153, v3, v85 dst_sel:DWORD dst_unused:UNUSED_PAD src0_sel:DWORD src1_sel:WORD_1
	v_or_b32_sdwa v152, v86, v2 dst_sel:DWORD dst_unused:UNUSED_PAD src0_sel:WORD_1 src1_sel:DWORD
	global_store_dwordx4 v[80:81], v[150:153], off offset:1024
	global_load_dwordx4 v[150:153], v[72:73], off
	global_load_dwordx4 v[160:163], v[72:73], off offset:16
	v_and_b32_e32 v4, 0xffff0000, v22
	v_lshlrev_b32_e32 v5, 16, v23
	v_lshlrev_b32_e32 v22, 16, v22
	v_and_b32_e32 v23, 0xffff0000, v23
	v_lshlrev_b32_e32 v164, 16, v24
	v_and_b32_e32 v165, 0xffff0000, v25
	v_and_b32_e32 v166, 0xffff0000, v18
	v_lshlrev_b32_e32 v167, 16, v19
	v_pk_mul_f32 v[18:19], v[148:149], v[136:137] op_sel_hi:[0,1]
	v_pk_mul_f32 v[136:137], v[148:149], v[138:139] op_sel_hi:[0,1]
	v_pk_mul_f32 v[138:139], v[148:149], v[142:143] op_sel_hi:[0,1]
	s_waitcnt vmcnt(1)
	v_mov_b32_e32 v24, v151
	v_mov_b32_e32 v25, v152
	s_waitcnt vmcnt(0)
; #define GAS __attribute__((address_space(1)))
; __device__ __forceinline__ void unpack8(v4u w, float (&f)[8]) { f[0] = bflo(w.x); f[1] = bfhi(w.x); f[2] = bflo(w.y); f[3] = bfhi(w.y); f[4] = bflo(w.z); f[5] = bfhi(w.z); f[6] = bflo(w.w); f[7] = bfhi(w.w); }
; __device__ __forceinline__ v4u pack8(const float (&o)[8]) { v4u w; w.x = pk2(o[0], o[1]); w.y = pk2(o[2], o[3]); w.z = pk2(o[4], o[5]); w.w = pk2(o[6], o[7]); return w; }
; template <bool XF32, bool FINAL, bool QUANT = false> ...
;     ...
;     for (int j = 0; j < 8; ++j) { const int c = 8 * lane + 512 * j; float yf[8], x[8]; unpack8(yraw[j], yf);
;         if (XF32) { x[0] = xf[j][0].x; x[1] = xf[j][0].y; x[2] = xf[j][0].z; x[3] = xf[j][0].w; x[4] = xf[j][1].x; x[5] = xf[j][1].y; x[6] = xf[j][1].z; x[7] = xf[j][1].w; }
;         else unpack8(xr[j], x);
;         const f32x4 g0 = *(const GAS f32x4*)(gpost + c), g1 = *(const GAS f32x4*)(gpost + c + 4);
; #pragma unroll
;         for (int e = 0; e < 4; ++e) { x[e] += yf[e] * rstd * g0[e]; x[4 + e] += yf[4 + e] * rstd * g1[e]; }
;         if (FINAL) { *(GAS f32x4*)(orow + c) = (f32x4){x[0], x[1], x[2], x[3]}; *(GAS f32x4*)(orow + c + 4) = (f32x4){x[4], x[5], x[6], x[7]}; }
;         else {
; #pragma unroll
;             for (int e = 0; e < 8; ++e) s2 += x[e] * x[e];
;             const v4u pw = pack8(x); *(GAS v4u*)(xbrow + c) = pw;
	v_mov_b32_e32 v132, v161
	v_mov_b32_e32 v133, v162
	v_mov_b32_e32 v151, v153
	v_mov_b32_e32 v161, v163
	v_pk_fma_f32 v[130:131], v[24:25], v[18:19], v[4:5]
	v_pk_fma_f32 v[24:25], v[132:133], v[20:21], v[134:135]
	v_pk_fma_f32 v[134:135], v[150:151], v[136:137], v[22:23]
	v_pk_fma_f32 v[132:133], v[160:161], v[138:139], v[164:165]
	v_and_b32_sdwa v4, v131, v203 dst_sel:DWORD dst_unused:UNUSED_PAD src0_sel:WORD_1 src1_sel:DWORD
	v_and_b32_sdwa v5, v130, v203 dst_sel:DWORD dst_unused:UNUSED_PAD src0_sel:WORD_1 src1_sel:DWORD
	v_and_b32_sdwa v18, v135, v203 dst_sel:DWORD dst_unused:UNUSED_PAD src0_sel:WORD_1 src1_sel:DWORD
	v_and_b32_sdwa v87, v24, v203 dst_sel:DWORD dst_unused:UNUSED_PAD src0_sel:WORD_1 src1_sel:DWORD
	v_and_b32_sdwa v115, v133, v203 dst_sel:DWORD dst_unused:UNUSED_PAD src0_sel:WORD_1 src1_sel:DWORD
	v_and_b32_sdwa v19, v134, v203 dst_sel:DWORD dst_unused:UNUSED_PAD src0_sel:WORD_1 src1_sel:DWORD
	v_and_b32_sdwa v22, v25, v203 dst_sel:DWORD dst_unused:UNUSED_PAD src0_sel:WORD_1 src1_sel:DWORD
	v_and_b32_sdwa v136, v132, v203 dst_sel:DWORD dst_unused:UNUSED_PAD src0_sel:WORD_1 src1_sel:DWORD
	v_add3_u32 v21, v131, v4, s14
	v_add3_u32 v4, v130, v5, s14
	v_add3_u32 v5, v135, v18, s14
	v_add3_u32 v87, v24, v87, s14
	v_add3_u32 v115, v133, v115, s14
	v_add3_u32 v20, v134, v19, s14
	v_add3_u32 v23, v25, v22, s14
	v_add3_u32 v22, v132, v136, s14
	v_and_b32_e32 v18, 0xffff0000, v4
	v_and_b32_e32 v19, 0xffff0000, v5
	v_and_b32_e32 v4, 0xffff0000, v87
	v_and_b32_e32 v5, 0xffff0000, v115
	v_or_b32_sdwa v137, v19, v21 dst_sel:DWORD dst_unused:UNUSED_PAD src0_sel:DWORD src1_sel:WORD_1
	v_or_b32_sdwa v136, v20, v18 dst_sel:DWORD dst_unused:UNUSED_PAD src0_sel:WORD_1 src1_sel:DWORD
	v_or_b32_sdwa v139, v5, v23 dst_sel:DWORD dst_unused:UNUSED_PAD src0_sel:DWORD src1_sel:WORD_1
	v_or_b32_sdwa v138, v22, v4 dst_sel:DWORD dst_unused:UNUSED_PAD src0_sel:WORD_1 src1_sel:DWORD
	global_store_dwordx4 v[80:81], v[136:139], off offset:2048
	global_load_dwordx4 v[142:145], v[74:75], off offset:16
	s_nop 0
	global_load_dwordx4 v[138:141], v[74:75], off
	v_add_f32_e32 v87, v182, v184
	v_add_f32_e32 v87, v185, v87
	v_add_f32_e32 v87, v183, v87
	v_add_f32_e32 v87, v194, v87
	v_add_f32_e32 v87, v196, v87
	v_add_f32_e32 v87, v197, v87
	v_pk_mul_f32 v[136:137], v[92:93], v[92:93]
	v_add_f32_e32 v87, v195, v87
	v_pk_mul_f32 v[150:151], v[88:89], v[88:89]
	v_add_f32_e32 v87, v136, v87
	v_add_f32_e32 v87, v150, v87
	v_add_f32_e32 v87, v151, v87
	v_pk_mul_f32 v[152:153], v[94:95], v[94:95]
	v_add_f32_e32 v87, v137, v87
	v_pk_mul_f32 v[160:161], v[90:91], v[90:91]
	v_add_f32_e32 v87, v152, v87
	v_add_f32_e32 v87, v160, v87
	v_add_f32_e32 v87, v161, v87
	v_add_f32_e32 v87, v153, v87
	v_pk_mul_f32 v[136:137], v[100:101], v[100:101]
	v_pk_mul_f32 v[150:151], v[96:97], v[96:97]
	v_add_f32_e32 v87, v136, v87
	v_add_f32_e32 v87, v150, v87
	v_add_f32_e32 v87, v151, v87
	v_pk_mul_f32 v[152:153], v[102:103], v[102:103]
	v_add_f32_e32 v87, v137, v87
	v_pk_mul_f32 v[160:161], v[98:99], v[98:99]
	v_add_f32_e32 v87, v152, v87
	v_add_f32_e32 v87, v160, v87
	v_add_f32_e32 v87, v161, v87
	v_add_f32_e32 v87, v153, v87
	v_pk_mul_f32 v[136:137], v[108:109], v[108:109]
	v_pk_mul_f32 v[150:151], v[104:105], v[104:105]
	v_add_f32_e32 v87, v136, v87
	v_add_f32_e32 v87, v150, v87
	v_add_f32_e32 v87, v151, v87
	v_pk_mul_f32 v[152:153], v[110:111], v[110:111]
	v_add_f32_e32 v87, v137, v87
	v_pk_mul_f32 v[160:161], v[106:107], v[106:107]
	v_add_f32_e32 v87, v152, v87
	v_add_f32_e32 v87, v160, v87
	v_add_f32_e32 v87, v161, v87
	v_add_f32_e32 v87, v153, v87
	v_pk_mul_f32 v[136:137], v[120:121], v[120:121]
	v_pk_mul_f32 v[150:151], v[116:117], v[116:117]
	v_add_f32_e32 v87, v136, v87
	v_add_f32_e32 v87, v150, v87
	v_add_f32_e32 v87, v151, v87
	v_pk_mul_f32 v[152:153], v[118:119], v[118:119]
	v_add_f32_e32 v87, v137, v87
	v_pk_mul_f32 v[160:161], v[112:113], v[112:113]
	v_add_f32_e32 v87, v152, v87
	v_add_f32_e32 v87, v160, v87
	v_add_f32_e32 v87, v161, v87
	v_add_f32_e32 v87, v153, v87
	v_pk_mul_f32 v[136:137], v[128:129], v[128:129]
	v_pk_mul_f32 v[150:151], v[124:125], v[124:125]
	v_add_f32_e32 v87, v136, v87
	v_add_f32_e32 v87, v150, v87
	v_add_f32_e32 v87, v151, v87
	v_pk_mul_f32 v[152:153], v[126:127], v[126:127]
	v_add_f32_e32 v87, v137, v87
	v_pk_mul_f32 v[160:161], v[122:123], v[122:123]
	v_add_f32_e32 v87, v152, v87
	v_add_f32_e32 v87, v160, v87
	v_add_f32_e32 v87, v161, v87
	v_add_f32_e32 v87, v153, v87
	v_pk_mul_f32 v[136:137], v[134:135], v[134:135]
	v_pk_mul_f32 v[150:151], v[130:131], v[130:131]
	v_add_f32_e32 v87, v136, v87
	v_add_f32_e32 v87, v150, v87
	v_add_f32_e32 v87, v151, v87
	v_pk_mul_f32 v[152:153], v[132:133], v[132:133]
	v_add_f32_e32 v87, v137, v87
	v_pk_mul_f32 v[160:161], v[24:25], v[24:25]
	v_add_f32_e32 v87, v152, v87
	v_add_f32_e32 v87, v160, v87
	v_add_f32_e32 v87, v161, v87
	v_add_f32_e32 v87, v153, v87
	s_waitcnt vmcnt(0)
; #define GAS __attribute__((address_space(1)))
; __device__ __forceinline__ v4u pack8(const float (&o)[8]) { v4u w; w.x = pk2(o[0], o[1]); w.y = pk2(o[2], o[3]); w.z = pk2(o[4], o[5]); w.w = pk2(o[6], o[7]); return w; }
; template <bool XF32, bool FINAL, bool QUANT = false> ...
;     ...
;             for (int e = 0; e < 8; ++e) s2 += x[e] * x[e];
;             const v4u pw = pack8(x); *(GAS v4u*)(xbrow + c) = pw;
;             if (QUANT) { xr[j] = pw;
; #pragma unroll
;                 for (int e = 0; e < 8; ++e) am = fmaxf(am, fabsf(x[e])); } }
;         if (j & 1) asm volatile("" ::: "memory"); }
;     if (!FINAL) { const float tot = wave_sum(s2, lane); const float rsn = 1.0f / sqrtf(tot * (1.0f / DM) + EPS); if (lane == 0) *rs_out = rsn;
	v_mov_b32_e32 v136, v139
	v_mov_b32_e32 v139, v141
	v_mov_b32_e32 v137, v140
	v_pk_fma_f32 v[140:141], v[138:139], v[146:147], v[168:169]
	v_mov_b32_e32 v150, v143
	v_mov_b32_e32 v151, v144
	v_mov_b32_e32 v143, v145
	v_pk_fma_f32 v[136:137], v[136:137], v[174:175], v[166:167]
	v_pk_mul_f32 v[144:145], v[140:141], v[140:141]
	v_pk_mul_f32 v[146:147], v[136:137], v[136:137]
	v_add_f32_e32 v87, v144, v87
	v_add_f32_e32 v87, v146, v87
	v_pk_fma_f32 v[142:143], v[142:143], v[178:179], v[172:173]
	v_add_f32_e32 v87, v147, v87
	v_pk_fma_f32 v[138:139], v[150:151], v[176:177], v[170:171]
	v_pk_mul_f32 v[150:151], v[142:143], v[142:143]
	v_add_f32_e32 v87, v145, v87
	v_pk_mul_f32 v[152:153], v[138:139], v[138:139]
	v_add_f32_e32 v87, v150, v87
	v_add_f32_e32 v87, v152, v87
	v_add_f32_e32 v87, v153, v87
	v_add_f32_e32 v87, v151, v87
	ds_bpermute_b32 v115, v154, v87
	v_and_b32_sdwa v144, v137, v203 dst_sel:DWORD dst_unused:UNUSED_PAD src0_sel:WORD_1 src1_sel:DWORD
	v_and_b32_sdwa v145, v136, v203 dst_sel:DWORD dst_unused:UNUSED_PAD src0_sel:WORD_1 src1_sel:DWORD
	v_and_b32_sdwa v146, v141, v203 dst_sel:DWORD dst_unused:UNUSED_PAD src0_sel:WORD_1 src1_sel:DWORD
	v_and_b32_sdwa v150, v138, v203 dst_sel:DWORD dst_unused:UNUSED_PAD src0_sel:WORD_1 src1_sel:DWORD
	s_waitcnt lgkmcnt(0)
	v_add_f32_e32 v87, v87, v115
	ds_bpermute_b32 v115, v155, v87
	v_and_b32_sdwa v153, v142, v203 dst_sel:DWORD dst_unused:UNUSED_PAD src0_sel:WORD_1 src1_sel:DWORD
	v_add3_u32 v160, v138, v150, s14
	v_add3_u32 v150, v142, v153, s14
	v_and_b32_sdwa v152, v143, v203 dst_sel:DWORD dst_unused:UNUSED_PAD src0_sel:WORD_1 src1_sel:DWORD
	s_waitcnt lgkmcnt(0)
	v_add_f32_e32 v87, v87, v115
	ds_bpermute_b32 v151, v156, v87
	v_add3_u32 v115, v137, v144, s14
	v_add3_u32 v144, v136, v145, s14
	v_add3_u32 v152, v143, v152, s14
	v_and_b32_sdwa v147, v140, v203 dst_sel:DWORD dst_unused:UNUSED_PAD src0_sel:WORD_1 src1_sel:DWORD
	s_waitcnt lgkmcnt(0)
	v_add_f32_e32 v87, v87, v151
	ds_bpermute_b32 v145, v157, v87
	v_add3_u32 v151, v141, v146, s14
	v_and_b32_sdwa v148, v139, v203 dst_sel:DWORD dst_unused:UNUSED_PAD src0_sel:WORD_1 src1_sel:DWORD
	v_add3_u32 v146, v140, v147, s14
	v_add3_u32 v147, v139, v148, s14
	s_waitcnt lgkmcnt(0)
	v_add_f32_e32 v87, v87, v145
	ds_bpermute_b32 v161, v158, v87
	v_and_b32_e32 v145, 0xffff0000, v151
	v_and_b32_e32 v148, 0xffff0000, v144
	v_and_b32_e32 v144, 0xffff0000, v160
	v_or_b32_sdwa v160, v146, v148 dst_sel:DWORD dst_unused:UNUSED_PAD src0_sel:WORD_1 src1_sel:DWORD
	s_waitcnt lgkmcnt(0)
	v_add_f32_e32 v151, v87, v161
	ds_bpermute_b32 v153, v159, v151
	v_and_b32_e32 v87, 0xffff0000, v152
	v_or_b32_sdwa v161, v145, v115 dst_sel:DWORD dst_unused:UNUSED_PAD src0_sel:DWORD src1_sel:WORD_1
	v_or_b32_sdwa v163, v87, v147 dst_sel:DWORD dst_unused:UNUSED_PAD src0_sel:DWORD src1_sel:WORD_1
	v_or_b32_sdwa v162, v150, v144 dst_sel:DWORD dst_unused:UNUSED_PAD src0_sel:WORD_1 src1_sel:DWORD
	s_waitcnt lgkmcnt(0)
	v_add_f32_e32 v151, v151, v153
	v_fmamk_f32 v151, v151, 0x39800000, v204
	v_mul_f32_e32 v152, 0x4f800000, v151
	v_cmp_gt_f32_e32 vcc, s73, v151
	global_store_dwordx4 v[80:81], v[160:163], off offset:3072
	s_nop 0
	v_cndmask_b32_e32 v151, v151, v152, vcc
	v_sqrt_f32_e32 v152, v151
	s_nop 0
	v_add_u32_e32 v80, -1, v152
	v_add_u32_e32 v81, 1, v152
	v_fma_f32 v153, -v80, v152, v151
	v_fma_f32 v160, -v81, v152, v151
	v_cmp_ge_f32_e64 s[44:45], 0, v153
	s_nop 1
	v_cndmask_b32_e64 v80, v152, v80, s[44:45]
	v_cmp_lt_f32_e64 s[44:45], 0, v160
	s_nop 1
	v_cndmask_b32_e64 v80, v80, v81, s[44:45]
	v_mul_f32_e32 v81, 0x37800000, v80
	v_cndmask_b32_e32 v80, v80, v81, vcc
	v_cmp_class_f32_e32 vcc, v151, v205
	s_nop 1
	v_cndmask_b32_e32 v80, v80, v151, vcc
	v_div_scale_f32 v81, s[12:13], v80, v80, 1.0
	v_rcp_f32_e32 v151, v81
	v_div_scale_f32 v152, vcc, 1.0, v80, 1.0
	v_fma_f32 v153, -v81, v151, 1.0
	v_fmac_f32_e32 v151, v153, v151
	v_mul_f32_e32 v153, v152, v151
	v_fma_f32 v160, -v81, v153, v152
	v_fmac_f32_e32 v153, v160, v151
	v_fma_f32 v81, -v81, v153, v152
	v_div_fmas_f32 v81, v81, v151, v153
	v_div_fixup_f32 v80, v81, v80, 1.0
	s_and_saveexec_b64 s[12:13], s[42:43]
	s_cbranch_execz .LBB0_637
	v_mov_b32_e32 v81, 0x120000
	global_store_dword v81, v80, s[34:35]

; #define GAS __attribute__((address_space(1)))
; __device__ __forceinline__ void unpack8(v4u w, float (&f)[8]) { f[0] = bflo(w.x); f[1] = bfhi(w.x); f[2] = bflo(w.y); f[3] = bfhi(w.y); f[4] = bflo(w.z); f[5] = bfhi(w.z); f[6] = bflo(w.w); f[7] = bfhi(w.w); }
; template <bool XF32, bool FINAL, bool QUANT = false> ...
;     v4u yraw[8]; f32x4 xf[8][2]; v4u xr[8]; float s = 0.f; float am = 0.f;
; #pragma unroll
;     for (int j = 0; j < 8; ++j) yraw[j] = *(const GAS v4u*)(yrow + 8 * lane + 512 * j);
; #pragma unroll
;     for (int j = 0; j < 8; ++j) {
;         if (XF32) { xf[j][0] = *(const GAS f32x4*)((const float*)xrow + 8 * lane + 512 * j); xf[j][1] = *(const GAS f32x4*)((const float*)xrow + 8 * lane + 512 * j + 4); }
;         else xr[j] = *(const GAS v4u*)((const bf16*)xrow + 8 * lane + 512 * j); }
; #pragma unroll
;     for (int j = 0; j < 8; ++j) { float yf[8]; unpack8(yraw[j], yf);
; #pragma unroll
;         for (int e = 0; e < 8; ++e) s += yf[e] * yf[e]; }
;     const float rstd = 1.0f / sqrtf(wave_sum(s, lane) * (1.0f / DM) + eps_y);
; __global__ void __launch_bounds__(NWAVES * 64, 2) enc_fwd(Args args) {
;     ...
;               else { for (int m = gw; m < M; m += NGW) { const float r_ = RF[m], r2_ = r_ * r_; float e4_ = r2_ * r2_; if ((I8D >> layer) & 1) { const float tm_ = __uint_as_float(RMAX[m]), hs_ = fmaxf(tm_ * tm_ * 1.0078125f, 1e-30f) * (1.0f / 255.0f); e4_ *= hs_ * hs_; } resid_row<false, true>(Y + (size_t)m * DM, XB + (size_t)m * DM, out + (size_t)m * DM, nullptr, nullptr, gpost, EPS / e4_, ln); } } }
.LBB0_936:
	v_lshl_add_u64 v[18:19], s[38:39], 0, v[62:63]
	v_add_co_u32_e32 v20, vcc, s66, v18
	s_add_u32 s10, s38, s8
	s_nop 0
	v_addc_co_u32_e32 v21, vcc, 0, v19, vcc
	v_add_co_u32_e32 v22, vcc, s52, v18
	s_addc_u32 s11, s39, s9
	s_nop 0
	v_addc_co_u32_e32 v23, vcc, 0, v19, vcc
	v_add_co_u32_e32 v24, vcc, s16, v18
	s_add_i32 s2, s2, s72
	s_nop 0
	v_addc_co_u32_e32 v25, vcc, 0, v19, vcc
	v_add_co_u32_e32 v18, vcc, s17, v18
	s_add_u32 s8, s8, s90
	s_nop 0
	v_addc_co_u32_e32 v19, vcc, 0, v19, vcc
	global_load_dword v66, v209, s[10:11]
	global_load_dwordx4 v[74:77], v[20:21], off offset:1024 nt
	global_load_dword v140, v208, s[10:11]
	global_load_dwordx4 v[42:45], v[22:23], off offset:3072 nt
	global_load_dwordx4 v[78:81], v[22:23], off offset:-4096 nt
	global_load_dwordx4 v[82:85], v[18:19], off offset:-4096 nt
	global_load_dwordx4 v[90:93], v[24:25], off offset:1024 nt
	global_load_dwordx4 v[110:113], v[20:21], off offset:2048 nt
	global_load_dwordx4 v[124:127], v[20:21], off offset:3072 nt
	global_load_dwordx4 v[148:151], v[22:23], off nt
	global_load_dwordx4 v[152:155], v[22:23], off offset:1024 nt
	global_load_dwordx4 v[46:49], v[22:23], off offset:2048 nt
	global_load_dwordx4 v[38:41], v[24:25], off offset:2048 nt
	global_load_dwordx4 v[34:37], v[24:25], off offset:3072 nt
	global_load_dwordx4 v[30:33], v[18:19], off nt
	global_load_dwordx4 v[26:29], v[18:19], off offset:1024 nt
	s_nop 0
	global_load_dwordx4 v[22:25], v[18:19], off offset:2048 nt
	s_nop 0
	global_load_dwordx4 v[18:21], v[18:19], off offset:3072 nt
	s_addc_u32 s9, s9, s91
	v_lshl_add_u64 v[62:63], v[62:63], 0, s[88:89]
	s_cmpk_lt_i32 s2, 0x4000
	s_waitcnt vmcnt(17)
	v_mul_f32_e32 v141, v66, v66
	s_waitcnt vmcnt(16)
	v_lshlrev_b32_e32 v108, 16, v76
	v_and_b32_e32 v109, 0xffff0000, v76
	v_lshlrev_b32_e32 v122, 16, v77
	s_waitcnt vmcnt(13)
	v_lshlrev_b32_e32 v120, 16, v78
	v_and_b32_e32 v121, 0xffff0000, v78
	v_lshlrev_b32_e32 v130, 16, v79
	v_and_b32_e32 v131, 0xffff0000, v79
	v_and_b32_e32 v123, 0xffff0000, v77
	s_waitcnt vmcnt(11)
	v_lshlrev_b32_e32 v132, 16, v90
	v_and_b32_e32 v133, 0xffff0000, v90
	v_lshlrev_b32_e32 v136, 16, v91
	v_and_b32_e32 v137, 0xffff0000, v91
	s_waitcnt vmcnt(7)
	v_lshlrev_b32_e32 v76, 16, v154
	v_and_b32_e32 v77, 0xffff0000, v154
	v_lshlrev_b32_e32 v90, 16, v155
	v_and_b32_e32 v91, 0xffff0000, v155
	v_mul_f32_e32 v141, 0x3f810000, v141
	v_pk_mul_f32 v[154:155], v[120:121], v[120:121]
	v_mov_b32_e32 v180, v140
	v_pk_mul_f32 v[156:157], v[130:131], v[130:131]
	v_max_f32_e32 v141, 0xda24260, v141
	v_add_f32_e32 v147, v154, v155
	v_lshlrev_b32_e32 v88, 16, v80
	v_and_b32_e32 v89, 0xffff0000, v80
	v_pk_mul_f32 v[140:141], v[140:141], v[180:181]
	v_add_f32_e32 v147, v156, v147
	v_lshlrev_b32_e32 v104, 16, v92
	v_and_b32_e32 v105, 0xffff0000, v92
	v_lshlrev_b32_e32 v118, 16, v93
	v_and_b32_e32 v119, 0xffff0000, v93
	v_lshlrev_b32_e32 v78, 16, v150
	v_and_b32_e32 v79, 0xffff0000, v150
	v_lshlrev_b32_e32 v92, 16, v151
	v_and_b32_e32 v93, 0xffff0000, v151
	v_pk_mul_f32 v[150:151], v[88:89], v[88:89]
	v_pk_mul_f32 v[140:141], v[140:141], v[140:141]
	v_add_f32_e32 v147, v157, v147
	v_lshlrev_b32_e32 v96, 16, v81
	v_and_b32_e32 v97, 0xffff0000, v81
	v_mul_f32_e32 v140, v140, v141
	v_add_f32_e32 v141, v150, v147
	v_lshlrev_b32_e32 v102, 16, v110
	v_and_b32_e32 v103, 0xffff0000, v110
	v_lshlrev_b32_e32 v106, 16, v111
	v_and_b32_e32 v107, 0xffff0000, v111
	v_lshlrev_b32_e32 v116, 16, v124
	v_and_b32_e32 v117, 0xffff0000, v124
	v_lshlrev_b32_e32 v128, 16, v125
	v_and_b32_e32 v129, 0xffff0000, v125
	v_lshlrev_b32_e32 v110, 16, v152
	v_and_b32_e32 v111, 0xffff0000, v152
	v_lshlrev_b32_e32 v124, 16, v153
	v_and_b32_e32 v125, 0xffff0000, v153
	v_pk_mul_f32 v[152:153], v[96:97], v[96:97]
	v_add_f32_e32 v141, v151, v141
	v_lshlrev_b32_e32 v134, 16, v74
	v_and_b32_e32 v135, 0xffff0000, v74
	v_add_f32_e32 v141, v152, v141
	v_pk_mul_f32 v[162:163], v[134:135], v[134:135]
	v_add_f32_e32 v141, v153, v141
	v_lshlrev_b32_e32 v138, 16, v75
	v_and_b32_e32 v139, 0xffff0000, v75
	v_add_f32_e32 v141, v162, v141
	v_pk_mul_f32 v[164:165], v[138:139], v[138:139]
	v_add_f32_e32 v141, v163, v141
	v_add_f32_e32 v141, v164, v141
	v_pk_mul_f32 v[158:159], v[108:109], v[108:109]
	v_add_f32_e32 v141, v165, v141
	v_add_f32_e32 v141, v158, v141
	v_pk_mul_f32 v[160:161], v[122:123], v[122:123]
	v_add_f32_e32 v141, v159, v141
	v_add_f32_e32 v141, v160, v141
	v_pk_mul_f32 v[170:171], v[102:103], v[102:103]
	v_add_f32_e32 v141, v161, v141
	v_add_f32_e32 v141, v170, v141
	v_pk_mul_f32 v[172:173], v[106:107], v[106:107]
	v_add_f32_e32 v141, v171, v141
	v_lshlrev_b32_e32 v74, 16, v112
	v_and_b32_e32 v75, 0xffff0000, v112
	v_add_f32_e32 v141, v172, v141
	v_pk_mul_f32 v[166:167], v[74:75], v[74:75]
	v_add_f32_e32 v141, v173, v141
	v_lshlrev_b32_e32 v80, 16, v113
	v_and_b32_e32 v81, 0xffff0000, v113
	v_add_f32_e32 v141, v166, v141
	v_pk_mul_f32 v[168:169], v[80:81], v[80:81]
	v_add_f32_e32 v141, v167, v141
	v_add_f32_e32 v141, v168, v141
	v_pk_mul_f32 v[178:179], v[116:117], v[116:117]
	v_add_f32_e32 v141, v169, v141
	v_add_f32_e32 v141, v178, v141
	v_pk_mul_f32 v[182:183], v[128:129], v[128:129]
	v_add_f32_e32 v141, v179, v141
	v_lshlrev_b32_e32 v70, 16, v84
	v_and_b32_e32 v71, 0xffff0000, v84
	v_lshlrev_b32_e32 v72, 16, v85
	v_and_b32_e32 v73, 0xffff0000, v85
	v_lshlrev_b32_e32 v84, 16, v126
	v_and_b32_e32 v85, 0xffff0000, v126
	v_add_f32_e32 v141, v182, v141
	v_pk_mul_f32 v[174:175], v[84:85], v[84:85]
	v_add_f32_e32 v141, v183, v141
	v_lshlrev_b32_e32 v94, 16, v127
	v_and_b32_e32 v95, 0xffff0000, v127
	v_add_f32_e32 v141, v174, v141
	v_pk_mul_f32 v[176:177], v[94:95], v[94:95]
	v_add_f32_e32 v141, v175, v141
	v_lshlrev_b32_e32 v112, 16, v148
	v_and_b32_e32 v113, 0xffff0000, v148
	v_add_f32_e32 v141, v176, v141
	v_pk_mul_f32 v[196:197], v[112:113], v[112:113]
	v_add_f32_e32 v141, v177, v141
	v_lshlrev_b32_e32 v126, 16, v149
	v_and_b32_e32 v127, 0xffff0000, v149
	v_add_f32_e32 v141, v196, v141
	v_pk_mul_f32 v[198:199], v[126:127], v[126:127]
	v_add_f32_e32 v141, v197, v141
	v_add_f32_e32 v141, v198, v141
	v_pk_mul_f32 v[184:185], v[78:79], v[78:79]
	v_add_f32_e32 v141, v199, v141
	v_add_f32_e32 v141, v184, v141
	v_pk_mul_f32 v[194:195], v[92:93], v[92:93]
	v_add_f32_e32 v141, v185, v141
	v_add_f32_e32 v141, v194, v141
	v_pk_mul_f32 v[216:217], v[110:111], v[110:111]
	v_add_f32_e32 v141, v195, v141
	v_add_f32_e32 v141, v216, v141
	v_pk_mul_f32 v[218:219], v[124:125], v[124:125]
	v_add_f32_e32 v141, v217, v141
	v_add_f32_e32 v141, v218, v141
	v_pk_mul_f32 v[200:201], v[76:77], v[76:77]
	v_add_f32_e32 v141, v219, v141
	v_add_f32_e32 v141, v200, v141
	v_pk_mul_f32 v[214:215], v[90:91], v[90:91]
	v_add_f32_e32 v141, v201, v141
	v_lshlrev_b32_e32 v86, 16, v82
	v_and_b32_e32 v87, 0xffff0000, v82
	v_lshlrev_b32_e32 v100, 16, v83
	v_and_b32_e32 v101, 0xffff0000, v83
	s_waitcnt vmcnt(6)
; #define GAS __attribute__((address_space(1)))
; __device__ __forceinline__ void unpack8(v4u w, float (&f)[8]) { f[0] = bflo(w.x); f[1] = bfhi(w.x); f[2] = bflo(w.y); f[3] = bfhi(w.y); f[4] = bflo(w.z); f[5] = bfhi(w.z); f[6] = bflo(w.w); f[7] = bfhi(w.w); }
; template <bool XF32, bool FINAL, bool QUANT = false> ...
;     ...
;     for (int j = 0; j < 8; ++j) { float yf[8]; unpack8(yraw[j], yf);
; #pragma unroll
;         for (int e = 0; e < 8; ++e) s += yf[e] * yf[e]; }
;     const float rstd = 1.0f / sqrtf(wave_sum(s, lane) * (1.0f / DM) + eps_y);
;     float s2 = 0.f;
; #pragma unroll
;     for (int j = 0; j < 8; ++j) { const int c = 8 * lane + 512 * j; float yf[8], x[8]; unpack8(yraw[j], yf);
;         if (XF32) { x[0] = xf[j][0].x; x[1] = xf[j][0].y; x[2] = xf[j][0].z; x[3] = xf[j][0].w; x[4] = xf[j][1].x; x[5] = xf[j][1].y; x[6] = xf[j][1].z; x[7] = xf[j][1].w; }
;         else unpack8(xr[j], x);
;         const f32x4 g0 = *(const GAS f32x4*)(gpost + c), g1 = *(const GAS f32x4*)(gpost + c + 4);
; #pragma unroll
;         for (int e = 0; e < 4; ++e) { x[e] += yf[e] * rstd * g0[e]; x[4 + e] += yf[4 + e] * rstd * g1[e]; }
;         if (FINAL) { *(GAS f32x4*)(orow + c) = (f32x4){x[0], x[1], x[2], x[3]}; *(GAS f32x4*)(orow + c + 4) = (f32x4){x[4], x[5], x[6], x[7]}; }
	v_lshlrev_b32_e32 v82, 16, v46
	v_and_b32_e32 v83, 0xffff0000, v46
	v_add_f32_e32 v141, v214, v141
	v_pk_mul_f32 v[224:225], v[82:83], v[82:83]
	v_add_f32_e32 v141, v215, v141
	v_lshlrev_b32_e32 v98, 16, v47
	v_and_b32_e32 v99, 0xffff0000, v47
	v_add_f32_e32 v141, v224, v141
	v_pk_mul_f32 v[226:227], v[98:99], v[98:99]
	v_add_f32_e32 v141, v225, v141
	v_lshlrev_b32_e32 v68, 16, v48
	v_and_b32_e32 v69, 0xffff0000, v48
	v_add_f32_e32 v141, v226, v141
	v_pk_mul_f32 v[220:221], v[68:69], v[68:69]
	v_add_f32_e32 v141, v227, v141
	v_lshlrev_b32_e32 v48, 16, v49
	v_and_b32_e32 v49, 0xffff0000, v49
	v_div_scale_f32 v147, s[10:11], v140, v140, s58
	v_add_f32_e32 v141, v220, v141
	v_pk_mul_f32 v[222:223], v[48:49], v[48:49]
	v_rcp_f32_e32 v151, v147
	v_add_f32_e32 v141, v221, v141
	v_and_b32_e32 v66, 0xffff0000, v45
	v_lshlrev_b32_e32 v67, 16, v45
	v_lshlrev_b32_e32 v46, 16, v44
	v_and_b32_e32 v47, 0xffff0000, v44
	v_lshlrev_b32_e32 v44, 16, v42
	v_and_b32_e32 v45, 0xffff0000, v42
	v_add_f32_e32 v141, v222, v141
	v_pk_mul_f32 v[230:231], v[44:45], v[44:45]
	v_add_f32_e32 v141, v223, v141
	v_lshlrev_b32_e32 v42, 16, v43
	v_and_b32_e32 v43, 0xffff0000, v43
	v_add_f32_e32 v141, v230, v141
	v_pk_mul_f32 v[232:233], v[42:43], v[42:43]
	v_fma_f32 v152, -v147, v151, 1.0
	v_add_f32_e32 v141, v231, v141
	v_div_scale_f32 v150, vcc, s58, v140, s58
	v_fmac_f32_e32 v151, v152, v151
	v_add_f32_e32 v141, v232, v141
	v_pk_mul_f32 v[228:229], v[46:47], v[46:47]
	v_mul_f32_e32 v152, v150, v151
	v_add_f32_e32 v141, v233, v141
	v_fma_f32 v153, -v147, v152, v150
	v_add_f32_e32 v141, v228, v141
	v_pk_mul_f32 v[148:149], v[66:67], v[66:67]
	v_fmac_f32_e32 v152, v153, v151
	v_add_f32_e32 v141, v229, v141
	v_fma_f32 v147, -v147, v152, v150
	v_add_f32_e32 v141, v149, v141
	v_div_fmas_f32 v147, v147, v151, v152
	v_add_f32_e32 v141, v148, v141
	v_div_fixup_f32 v140, v147, v140, s58
	ds_bpermute_b32 v147, v115, v141
	s_waitcnt lgkmcnt(0)
	v_add_f32_e32 v141, v141, v147
	ds_bpermute_b32 v147, v142, v141
	s_waitcnt lgkmcnt(0)
	v_add_f32_e32 v141, v141, v147
	ds_bpermute_b32 v147, v143, v141
	s_waitcnt lgkmcnt(0)
	v_add_f32_e32 v141, v141, v147
	ds_bpermute_b32 v147, v144, v141
	s_waitcnt lgkmcnt(0)
	v_add_f32_e32 v141, v141, v147
	ds_bpermute_b32 v147, v145, v141
	s_waitcnt lgkmcnt(0)
	v_add_f32_e32 v141, v141, v147
	ds_bpermute_b32 v147, v146, v141
	s_waitcnt lgkmcnt(0)
	v_add_f32_e32 v141, v141, v147
	v_fmac_f32_e32 v140, 0x39800000, v141
	v_mul_f32_e32 v141, 0x4f800000, v140
	v_cmp_gt_f32_e32 vcc, s73, v140
	s_nop 1
	v_cndmask_b32_e32 v140, v140, v141, vcc
	v_sqrt_f32_e32 v141, v140
	s_nop 0
	v_add_u32_e32 v147, -1, v141
	v_add_u32_e32 v148, 1, v141
	v_fma_f32 v149, -v147, v141, v140
	v_fma_f32 v150, -v148, v141, v140
	v_cmp_ge_f32_e64 s[42:43], 0, v149
	s_nop 1
	v_cndmask_b32_e64 v141, v141, v147, s[42:43]
	v_cmp_lt_f32_e64 s[42:43], 0, v150
	s_nop 1
	v_cndmask_b32_e64 v141, v141, v148, s[42:43]
	v_mul_f32_e32 v147, 0x37800000, v141
	v_cndmask_b32_e32 v141, v141, v147, vcc
	v_cmp_class_f32_e32 vcc, v140, v205
	s_nop 1
	v_cndmask_b32_e32 v140, v141, v140, vcc
	v_div_scale_f32 v141, s[10:11], v140, v140, 1.0
	v_rcp_f32_e32 v148, v141
	v_div_scale_f32 v147, vcc, 1.0, v140, 1.0
	v_fma_f32 v149, -v141, v148, 1.0
	v_fmac_f32_e32 v148, v149, v148
	v_mul_f32_e32 v149, v147, v148
	v_fma_f32 v150, -v141, v149, v147
	v_fmac_f32_e32 v149, v150, v148
	v_fma_f32 v141, -v141, v149, v147
	v_div_fmas_f32 v141, v141, v148, v149
	v_div_fixup_f32 v140, v141, v140, 1.0
	v_pk_mul_f32 v[120:121], v[140:141], v[120:121] op_sel_hi:[0,1]
	v_pk_mul_f32 v[88:89], v[140:141], v[88:89] op_sel_hi:[0,1]
	v_pk_mul_f32 v[130:131], v[140:141], v[130:131] op_sel_hi:[0,1]
	v_pk_mul_f32 v[96:97], v[140:141], v[96:97] op_sel_hi:[0,1]
	v_pk_mul_f32 v[134:135], v[140:141], v[134:135] op_sel_hi:[0,1]
	v_pk_mul_f32 v[108:109], v[140:141], v[108:109] op_sel_hi:[0,1]
	v_pk_mul_f32 v[138:139], v[140:141], v[138:139] op_sel_hi:[0,1]
	v_pk_mul_f32 v[148:149], v[140:141], v[122:123] op_sel_hi:[0,1]
	v_pk_fma_f32 v[86:87], v[2:3], v[120:121], v[86:87]
	v_pk_fma_f32 v[70:71], v[6:7], v[88:89], v[70:71]
	v_pk_fma_f32 v[88:89], v[4:5], v[130:131], v[100:101]
	v_pk_fma_f32 v[72:73], v[8:9], v[96:97], v[72:73]
	v_pk_fma_f32 v[120:121], v[10:11], v[134:135], v[132:133]
	v_pk_fma_f32 v[130:131], v[14:15], v[108:109], v[104:105]
	v_pk_fma_f32 v[122:123], v[12:13], v[138:139], v[136:137]
	v_pk_fma_f32 v[132:133], v[16:17], v[148:149], v[118:119]
	global_store_dwordx4 v[64:65], v[86:89], off
	global_store_dwordx4 v[64:65], v[70:73], off offset:16
	global_store_dwordx4 v[64:65], v[120:123], off offset:2048
	global_store_dwordx4 v[64:65], v[130:133], off offset:2064
	global_load_dwordx4 v[70:73], v[50:51], off
	global_load_dwordx4 v[86:89], v[50:51], off offset:16
	v_add_co_u32_e32 v96, vcc, s82, v64
	s_waitcnt vmcnt(11)
	v_lshlrev_b32_e32 v104, 16, v40
	v_addc_co_u32_e32 v97, vcc, 0, v65, vcc
	v_add_co_u32_e32 v100, vcc, s83, v64
	v_and_b32_e32 v105, 0xffff0000, v40
	v_lshlrev_b32_e32 v108, 16, v41
	v_and_b32_e32 v109, 0xffff0000, v41
	v_lshlrev_b32_e32 v40, 16, v38
	v_and_b32_e32 v41, 0xffff0000, v38
	v_lshlrev_b32_e32 v118, 16, v39
	v_and_b32_e32 v119, 0xffff0000, v39
	v_pk_mul_f32 v[38:39], v[140:141], v[102:103] op_sel_hi:[0,1]
	v_pk_mul_f32 v[102:103], v[140:141], v[106:107] op_sel_hi:[0,1]
	v_addc_co_u32_e32 v101, vcc, 0, v65, vcc
	v_pk_mul_f32 v[74:75], v[140:141], v[74:75] op_sel_hi:[0,1]
	v_pk_mul_f32 v[80:81], v[140:141], v[80:81] op_sel_hi:[0,1]
	v_pk_mul_f32 v[84:85], v[140:141], v[84:85] op_sel_hi:[0,1]
	v_pk_mul_f32 v[94:95], v[140:141], v[94:95] op_sel_hi:[0,1]
	v_pk_mul_f32 v[78:79], v[140:141], v[78:79] op_sel_hi:[0,1]
	v_pk_mul_f32 v[68:69], v[140:141], v[68:69] op_sel_hi:[0,1]
	v_pk_mul_f32 v[48:49], v[140:141], v[48:49] op_sel_hi:[0,1]
	s_waitcnt vmcnt(1)
; #define GAS __attribute__((address_space(1)))
; __device__ __forceinline__ void unpack8(v4u w, float (&f)[8]) { f[0] = bflo(w.x); f[1] = bfhi(w.x); f[2] = bflo(w.y); f[3] = bfhi(w.y); f[4] = bflo(w.z); f[5] = bfhi(w.z); f[6] = bflo(w.w); f[7] = bfhi(w.w); }
; template <bool XF32, bool FINAL, bool QUANT = false> ...
;     ...
;     for (int j = 0; j < 8; ++j) { const int c = 8 * lane + 512 * j; float yf[8], x[8]; unpack8(yraw[j], yf);
;         if (XF32) { x[0] = xf[j][0].x; x[1] = xf[j][0].y; x[2] = xf[j][0].z; x[3] = xf[j][0].w; x[4] = xf[j][1].x; x[5] = xf[j][1].y; x[6] = xf[j][1].z; x[7] = xf[j][1].w; }
;         else unpack8(xr[j], x);
;         const f32x4 g0 = *(const GAS f32x4*)(gpost + c), g1 = *(const GAS f32x4*)(gpost + c + 4);
; #pragma unroll
;         for (int e = 0; e < 4; ++e) { x[e] += yf[e] * rstd * g0[e]; x[4 + e] += yf[4 + e] * rstd * g1[e]; }
;         if (FINAL) { *(GAS f32x4*)(orow + c) = (f32x4){x[0], x[1], x[2], x[3]}; *(GAS f32x4*)(orow + c + 4) = (f32x4){x[4], x[5], x[6], x[7]}; }
	v_pk_fma_f32 v[38:39], v[70:71], v[38:39], v[40:41]
	v_pk_fma_f32 v[40:41], v[72:73], v[102:103], v[118:119]
	s_waitcnt vmcnt(0)
	v_pk_fma_f32 v[70:71], v[86:87], v[74:75], v[104:105]
	v_pk_fma_f32 v[72:73], v[88:89], v[80:81], v[108:109]
	global_store_dwordx4 v[100:101], v[38:41], off offset:-4096
	global_store_dwordx4 v[96:97], v[70:73], off offset:16
	global_load_dwordx4 v[38:41], v[52:53], off
	s_nop 0
	global_load_dwordx4 v[70:73], v[52:53], off offset:16
	v_lshlrev_b32_e32 v74, 16, v36
	v_and_b32_e32 v75, 0xffff0000, v36
	v_lshlrev_b32_e32 v80, 16, v37
	v_and_b32_e32 v81, 0xffff0000, v37
	v_lshlrev_b32_e32 v36, 16, v34
	v_and_b32_e32 v37, 0xffff0000, v34
	v_lshlrev_b32_e32 v86, 16, v35
	v_and_b32_e32 v87, 0xffff0000, v35
	v_pk_mul_f32 v[34:35], v[140:141], v[116:117] op_sel_hi:[0,1]
	v_pk_mul_f32 v[88:89], v[140:141], v[128:129] op_sel_hi:[0,1]
	s_waitcnt vmcnt(1)
	v_pk_fma_f32 v[34:35], v[38:39], v[34:35], v[36:37]
	v_pk_fma_f32 v[36:37], v[40:41], v[88:89], v[86:87]
	s_waitcnt vmcnt(0)
	v_pk_fma_f32 v[38:39], v[70:71], v[84:85], v[74:75]
	v_pk_fma_f32 v[40:41], v[72:73], v[94:95], v[80:81]
	global_store_dwordx4 v[96:97], v[34:37], off offset:2048
	global_store_dwordx4 v[96:97], v[38:41], off offset:2064
	global_load_dwordx4 v[34:37], v[54:55], off
	global_load_dwordx4 v[38:41], v[54:55], off offset:16
	v_lshlrev_b32_e32 v70, 16, v32
	v_and_b32_e32 v71, 0xffff0000, v32
	v_lshlrev_b32_e32 v72, 16, v33
	v_and_b32_e32 v73, 0xffff0000, v33
	v_lshlrev_b32_e32 v32, 16, v30
	v_and_b32_e32 v33, 0xffff0000, v30
	v_lshlrev_b32_e32 v74, 16, v31
	v_and_b32_e32 v75, 0xffff0000, v31
	v_pk_mul_f32 v[30:31], v[140:141], v[112:113] op_sel_hi:[0,1]
	v_pk_mul_f32 v[80:81], v[140:141], v[126:127] op_sel_hi:[0,1]
	v_pk_mul_f32 v[84:85], v[140:141], v[92:93] op_sel_hi:[0,1]
	s_waitcnt vmcnt(1)
	v_pk_fma_f32 v[30:31], v[34:35], v[30:31], v[32:33]
	v_pk_fma_f32 v[32:33], v[36:37], v[80:81], v[74:75]
	s_waitcnt vmcnt(0)
	v_pk_fma_f32 v[34:35], v[38:39], v[78:79], v[70:71]
	v_pk_fma_f32 v[36:37], v[40:41], v[84:85], v[72:73]
	global_store_dwordx4 v[100:101], v[30:33], off
	global_store_dwordx4 v[100:101], v[34:37], off offset:16
	global_load_dwordx4 v[30:33], v[56:57], off
	s_nop 0
	global_load_dwordx4 v[34:37], v[56:57], off offset:16
	v_lshlrev_b32_e32 v38, 16, v28
	v_and_b32_e32 v39, 0xffff0000, v28
	v_lshlrev_b32_e32 v40, 16, v29
	v_and_b32_e32 v41, 0xffff0000, v29
	v_lshlrev_b32_e32 v28, 16, v26
	v_and_b32_e32 v29, 0xffff0000, v26
	v_lshlrev_b32_e32 v70, 16, v27
	v_and_b32_e32 v71, 0xffff0000, v27
	v_pk_mul_f32 v[26:27], v[140:141], v[110:111] op_sel_hi:[0,1]
	v_pk_mul_f32 v[74:75], v[140:141], v[124:125] op_sel_hi:[0,1]
	v_pk_mul_f32 v[72:73], v[140:141], v[76:77] op_sel_hi:[0,1]
	v_pk_mul_f32 v[76:77], v[140:141], v[90:91] op_sel_hi:[0,1]
	s_waitcnt vmcnt(1)
	v_pk_fma_f32 v[26:27], v[30:31], v[26:27], v[28:29]
	v_pk_fma_f32 v[28:29], v[32:33], v[74:75], v[70:71]
	s_waitcnt vmcnt(0)
	v_pk_fma_f32 v[30:31], v[34:35], v[72:73], v[38:39]
	v_pk_fma_f32 v[32:33], v[36:37], v[76:77], v[40:41]
	global_store_dwordx4 v[100:101], v[26:29], off offset:2048
	global_store_dwordx4 v[100:101], v[30:33], off offset:2064
	global_load_dwordx4 v[26:29], v[58:59], off
	global_load_dwordx4 v[30:33], v[58:59], off offset:16
	v_add_co_u32_e32 v34, vcc, s76, v64
	v_lshlrev_b32_e32 v36, 16, v24
	v_and_b32_e32 v37, 0xffff0000, v24
	v_lshlrev_b32_e32 v38, 16, v25
	v_and_b32_e32 v39, 0xffff0000, v25
	v_lshlrev_b32_e32 v24, 16, v22
	v_and_b32_e32 v25, 0xffff0000, v22
	v_lshlrev_b32_e32 v40, 16, v23
	v_and_b32_e32 v41, 0xffff0000, v23
	v_pk_mul_f32 v[22:23], v[140:141], v[82:83] op_sel_hi:[0,1]
	v_pk_mul_f32 v[70:71], v[140:141], v[98:99] op_sel_hi:[0,1]
	v_addc_co_u32_e32 v35, vcc, 0, v65, vcc
	v_lshl_add_u64 v[64:65], v[64:65], 0, s[12:13]
	s_waitcnt vmcnt(1)
	v_pk_fma_f32 v[22:23], v[26:27], v[22:23], v[24:25]
	v_pk_fma_f32 v[24:25], v[28:29], v[70:71], v[40:41]
	s_waitcnt vmcnt(0)
	v_pk_fma_f32 v[26:27], v[30:31], v[68:69], v[36:37]
	v_pk_fma_f32 v[28:29], v[32:33], v[48:49], v[38:39]
	global_store_dwordx4 v[34:35], v[22:25], off
	global_store_dwordx4 v[34:35], v[26:29], off offset:16
	global_load_dwordx4 v[22:25], v[60:61], off
	s_nop 0
	global_load_dwordx4 v[26:29], v[60:61], off offset:16
	v_lshlrev_b32_e32 v30, 16, v20
	v_and_b32_e32 v31, 0xffff0000, v20
	v_lshlrev_b32_e32 v32, 16, v18
	v_and_b32_e32 v33, 0xffff0000, v18
	v_lshlrev_b32_e32 v36, 16, v19
	v_and_b32_e32 v37, 0xffff0000, v19
	v_lshlrev_b32_e32 v38, 16, v21
	v_and_b32_e32 v39, 0xffff0000, v21
	v_pk_mul_f32 v[18:19], v[140:141], v[44:45] op_sel_hi:[0,1]
	v_pk_mul_f32 v[20:21], v[140:141], v[46:47] op_sel_hi:[0,1]
	v_pk_mul_f32 v[40:41], v[140:141], v[42:43] op_sel_hi:[0,1]
	v_pk_mul_f32 v[42:43], v[140:141], v[66:67] op_sel_hi:[0,1]
	s_waitcnt vmcnt(1)
	v_pk_fma_f32 v[18:19], v[22:23], v[18:19], v[32:33]
	s_waitcnt vmcnt(0)
	v_pk_fma_f32 v[22:23], v[26:27], v[20:21], v[30:31]
	v_pk_fma_f32 v[20:21], v[24:25], v[40:41], v[36:37]
	v_pk_fma_f32 v[24:25], v[28:29], v[42:43], v[38:39] op_sel:[0,1,0] op_sel_hi:[1,0,1]
	global_store_dwordx4 v[34:35], v[18:21], off offset:2048
	global_store_dwordx4 v[34:35], v[22:25], off offset:2064
	s_cbranch_scc1 .LBB0_936

; #define GAS __attribute__((address_space(1)))
; __device__ __forceinline__ void unpack8(v4u w, float (&f)[8]) { f[0] = bflo(w.x); f[1] = bfhi(w.x); f[2] = bflo(w.y); f[3] = bfhi(w.y); f[4] = bflo(w.z); f[5] = bfhi(w.z); f[6] = bflo(w.w); f[7] = bfhi(w.w); }
; template <bool XF32, bool FINAL, bool QUANT = false> ...
;     v4u yraw[8]; f32x4 xf[8][2]; v4u xr[8]; float s = 0.f; float am = 0.f;
; #pragma unroll
;     for (int j = 0; j < 8; ++j) yraw[j] = *(const GAS v4u*)(yrow + 8 * lane + 512 * j);
; #pragma unroll
;     for (int j = 0; j < 8; ++j) {
;         if (XF32) { xf[j][0] = *(const GAS f32x4*)((const float*)xrow + 8 * lane + 512 * j); xf[j][1] = *(const GAS f32x4*)((const float*)xrow + 8 * lane + 512 * j + 4); }
;         else xr[j] = *(const GAS v4u*)((const bf16*)xrow + 8 * lane + 512 * j); }
; #pragma unroll
;     for (int j = 0; j < 8; ++j) { float yf[8]; unpack8(yraw[j], yf);
; #pragma unroll
;         for (int e = 0; e < 8; ++e) s += yf[e] * yf[e]; }
;     const float rstd = 1.0f / sqrtf(wave_sum(s, lane) * (1.0f / DM) + eps_y);
; __global__ void __launch_bounds__(NWAVES * 64, 2) enc_fwd(Args args) {
;     ...
;               if (layer + 1 < N_LAYERS) { for (int m = gw; m < M; m += NGW) { const float r_ = RF[m], r2_ = r_ * r_; float e4_ = r2_ * r2_; if ((I8D >> layer) & 1) { const float tm_ = __uint_as_float(RMAX[m]), hs_ = fmaxf(tm_ * tm_ * 1.0078125f, 1e-30f) * (1.0f / 255.0f); e4_ *= hs_ * hs_; } if ((I8P >> (layer + 1)) & 1) resid_row<false, false, true>(Y + (size_t)m * DM, XB + (size_t)m * DM, nullptr, XB + (size_t)m * DM, RS + m, gpost, EPS / e4_, ln, XQ + (size_t)m * DM, RF + m);
.LBB0_942:
	v_lshl_add_u64 v[2:3], s[38:39], 0, v[58:59]
	s_add_u32 s8, s38, s6
	v_add_co_u32_e32 v4, vcc, s52, v2
	s_addc_u32 s9, s39, s7
	s_nop 0
	v_addc_co_u32_e32 v5, vcc, 0, v3, vcc
	global_load_dword v94, v208, s[8:9]
	global_load_dword v1, v209, s[8:9]
	global_load_dwordx4 v[6:9], v[4:5], off offset:3072 nt
	global_load_dwordx4 v[18:21], v[4:5], off offset:-4096 nt
	v_add_co_u32_e32 v10, vcc, s66, v2
	s_waitcnt vmcnt(3)
	v_mov_b32_e32 v180, v94
	v_addc_co_u32_e32 v11, vcc, 0, v3, vcc
	global_load_dwordx4 v[26:29], v[10:11], off offset:1024 nt
	global_load_dwordx4 v[80:83], v[10:11], off offset:2048 nt
	global_load_dwordx4 v[86:89], v[10:11], off offset:3072 nt
	global_load_dwordx4 v[90:93], v[4:5], off nt
	v_add_co_u32_e32 v84, vcc, s46, v2
	s_waitcnt vmcnt(4)
	v_and_b32_e32 v70, 0xffff0000, v18
	v_addc_co_u32_e32 v85, vcc, 0, v3, vcc
	v_add_co_u32_e32 v62, vcc, s47, v2
	v_lshlrev_b32_e32 v71, 16, v19
	s_nop 0
	v_addc_co_u32_e32 v63, vcc, 0, v3, vcc
	global_load_dwordx4 v[142:145], v[4:5], off offset:1024 nt
	global_load_dwordx4 v[10:13], v[4:5], off offset:2048 nt
	global_load_dwordx4 v[22:25], v[62:63], off offset:-4096 nt
	global_load_dwordx4 v[14:17], v[84:85], off offset:1024 nt
	s_nop 0
	global_load_dwordx4 v[2:5], v[84:85], off offset:3072 nt
	v_lshlrev_b32_e32 v66, 16, v18
	v_and_b32_e32 v67, 0xffff0000, v19
	v_and_b32_e32 v78, 0xffff0000, v20
	v_lshlrev_b32_e32 v79, 16, v21
	v_lshlrev_b32_e32 v72, 16, v20
	v_and_b32_e32 v73, 0xffff0000, v21
	v_pk_mul_f32 v[18:19], v[66:67], v[66:67]
	v_pk_mul_f32 v[20:21], v[70:71], v[70:71]
	v_mul_f32_e32 v1, v1, v1
	v_add_f32_e32 v18, v18, v20
	v_add_f32_e32 v18, v21, v18
	v_add_f32_e32 v18, v19, v18
	v_mul_f32_e32 v1, 0x3f810000, v1
	v_max_f32_e32 v95, 0xda24260, v1
	v_lshlrev_b32_e32 v158, 16, v6
	v_and_b32_e32 v159, 0xffff0000, v7
	v_and_b32_e32 v156, 0xffff0000, v6
	v_lshlrev_b32_e32 v157, 16, v7
	v_pk_mul_f32 v[6:7], v[158:159], v[158:159]
	v_pk_mul_f32 v[196:197], v[156:157], v[156:157]
	v_lshlrev_b32_e32 v134, 16, v8
	v_and_b32_e32 v136, 0xffff0000, v8
	v_and_b32_e32 v138, 0xffff0000, v9
	v_lshlrev_b32_e32 v139, 16, v9
	v_pk_mul_f32 v[8:9], v[138:139], v[138:139]
	v_mov_b32_e32 v137, v139
	s_waitcnt vmcnt(8)
	v_and_b32_e32 v100, 0xffff0000, v26
	v_lshlrev_b32_e32 v101, 16, v27
	v_lshlrev_b32_e32 v68, 16, v26
	v_and_b32_e32 v69, 0xffff0000, v27
	v_pk_mul_f32 v[26:27], v[72:73], v[72:73]
	v_and_b32_e32 v102, 0xffff0000, v28
	v_lshlrev_b32_e32 v103, 16, v29
	v_lshlrev_b32_e32 v106, 16, v28
	v_and_b32_e32 v107, 0xffff0000, v29
	v_pk_mul_f32 v[28:29], v[78:79], v[78:79]
	v_add_f32_e32 v18, v26, v18
	v_add_f32_e32 v18, v28, v18
	v_add_f32_e32 v18, v29, v18
	s_waitcnt vmcnt(7)
	v_and_b32_e32 v74, 0xffff0000, v80
	v_lshlrev_b32_e32 v75, 16, v81
	v_lshlrev_b32_e32 v64, 16, v80
	v_and_b32_e32 v65, 0xffff0000, v81
	v_pk_mul_f32 v[80:81], v[68:69], v[68:69]
	v_add_f32_e32 v18, v27, v18
	v_and_b32_e32 v110, 0xffff0000, v82
	v_lshlrev_b32_e32 v111, 16, v83
	v_lshlrev_b32_e32 v116, 16, v82
	v_and_b32_e32 v117, 0xffff0000, v83
	v_pk_mul_f32 v[82:83], v[100:101], v[100:101]
	v_add_f32_e32 v18, v80, v18
	v_add_f32_e32 v18, v82, v18
	v_add_f32_e32 v18, v83, v18
	v_pk_mul_f32 v[104:105], v[106:107], v[106:107]
	v_add_f32_e32 v18, v81, v18
	v_pk_mul_f32 v[108:109], v[102:103], v[102:103]
	v_add_f32_e32 v18, v104, v18
	v_add_f32_e32 v18, v108, v18
	v_add_f32_e32 v18, v109, v18
	v_pk_mul_f32 v[112:113], v[64:65], v[64:65]
	v_add_f32_e32 v18, v105, v18
	v_pk_mul_f32 v[122:123], v[74:75], v[74:75]
	v_add_f32_e32 v18, v112, v18
	v_add_f32_e32 v18, v122, v18
	v_add_f32_e32 v18, v123, v18
	v_pk_mul_f32 v[132:133], v[116:117], v[116:117]
	v_add_f32_e32 v18, v113, v18
	v_pk_mul_f32 v[146:147], v[110:111], v[110:111]
	v_add_f32_e32 v18, v132, v18
	v_add_f32_e32 v18, v146, v18
	s_waitcnt vmcnt(6)
	v_lshlrev_b32_e32 v76, 16, v86
	v_and_b32_e32 v77, 0xffff0000, v87
	v_add_f32_e32 v18, v147, v18
	v_and_b32_e32 v118, 0xffff0000, v86
	v_lshlrev_b32_e32 v119, 16, v87
	v_pk_mul_f32 v[160:161], v[76:77], v[76:77]
	v_add_f32_e32 v18, v133, v18
	v_pk_mul_f32 v[170:171], v[118:119], v[118:119]
	v_add_f32_e32 v18, v160, v18
	v_add_f32_e32 v18, v170, v18
	v_lshlrev_b32_e32 v124, 16, v88
	v_and_b32_e32 v125, 0xffff0000, v89
	v_add_f32_e32 v18, v171, v18
	v_and_b32_e32 v120, 0xffff0000, v88
	v_lshlrev_b32_e32 v121, 16, v89
	v_pk_mul_f32 v[88:89], v[124:125], v[124:125]
	v_add_f32_e32 v18, v161, v18
	v_pk_mul_f32 v[86:87], v[94:95], v[180:181]
	v_pk_mul_f32 v[94:95], v[120:121], v[120:121]
	v_add_f32_e32 v18, v88, v18
	v_pk_mul_f32 v[86:87], v[86:87], v[86:87]
	v_add_f32_e32 v18, v94, v18
	v_mul_f32_e32 v1, v86, v87
	s_waitcnt vmcnt(5)
	v_lshlrev_b32_e32 v86, 16, v90
	v_and_b32_e32 v87, 0xffff0000, v91
	v_add_f32_e32 v18, v95, v18
	v_and_b32_e32 v126, 0xffff0000, v90
	v_lshlrev_b32_e32 v127, 16, v91
	v_pk_mul_f32 v[90:91], v[86:87], v[86:87]
	v_add_f32_e32 v18, v89, v18
	v_pk_mul_f32 v[172:173], v[126:127], v[126:127]
	v_add_f32_e32 v18, v90, v18
	v_add_f32_e32 v18, v172, v18
	v_lshlrev_b32_e32 v128, 16, v92
	v_and_b32_e32 v129, 0xffff0000, v93
	v_add_f32_e32 v18, v173, v18
	v_and_b32_e32 v130, 0xffff0000, v92
	v_lshlrev_b32_e32 v131, 16, v93
	v_pk_mul_f32 v[92:93], v[128:129], v[128:129]
	v_add_f32_e32 v18, v91, v18
	v_pk_mul_f32 v[174:175], v[130:131], v[130:131]
	v_add_f32_e32 v18, v92, v18
	v_add_f32_e32 v18, v174, v18
	s_waitcnt vmcnt(4)
; #define GAS __attribute__((address_space(1)))
; __device__ __forceinline__ void unpack8(v4u w, float (&f)[8]) { f[0] = bflo(w.x); f[1] = bfhi(w.x); f[2] = bflo(w.y); f[3] = bfhi(w.y); f[4] = bflo(w.z); f[5] = bfhi(w.z); f[6] = bflo(w.w); f[7] = bfhi(w.w); }
; template <bool XF32, bool FINAL, bool QUANT = false> ...
;     ...
; #pragma unroll
;     for (int j = 0; j < 8; ++j) yraw[j] = *(const GAS v4u*)(yrow + 8 * lane + 512 * j);
; #pragma unroll
;     for (int j = 0; j < 8; ++j) {
;         if (XF32) { xf[j][0] = *(const GAS f32x4*)((const float*)xrow + 8 * lane + 512 * j); xf[j][1] = *(const GAS f32x4*)((const float*)xrow + 8 * lane + 512 * j + 4); }
;         else xr[j] = *(const GAS v4u*)((const bf16*)xrow + 8 * lane + 512 * j); }
; #pragma unroll
;     for (int j = 0; j < 8; ++j) { float yf[8]; unpack8(yraw[j], yf);
; #pragma unroll
;         for (int e = 0; e < 8; ++e) s += yf[e] * yf[e]; }
;     const float rstd = 1.0f / sqrtf(wave_sum(s, lane) * (1.0f / DM) + eps_y);
; __global__ void __launch_bounds__(NWAVES * 64, 2) enc_fwd(Args args) {
;     ...
;               if (layer + 1 < N_LAYERS) { for (int m = gw; m < M; m += NGW) { const float r_ = RF[m], r2_ = r_ * r_; float e4_ = r2_ * r2_; if ((I8D >> layer) & 1) { const float tm_ = __uint_as_float(RMAX[m]), hs_ = fmaxf(tm_ * tm_ * 1.0078125f, 1e-30f) * (1.0f / 255.0f); e4_ *= hs_ * hs_; } if ((I8P >> (layer + 1)) & 1) resid_row<false, false, true>(Y + (size_t)m * DM, XB + (size_t)m * DM, nullptr, XB + (size_t)m * DM, RS + m, gpost, EPS / e4_, ln, XQ + (size_t)m * DM, RF + m);
	v_lshlrev_b32_e32 v96, 16, v142
	v_and_b32_e32 v97, 0xffff0000, v143
	v_add_f32_e32 v18, v175, v18
	v_and_b32_e32 v98, 0xffff0000, v142
	v_lshlrev_b32_e32 v99, 16, v143
	v_pk_mul_f32 v[176:177], v[96:97], v[96:97]
	v_add_f32_e32 v18, v93, v18
	v_pk_mul_f32 v[178:179], v[98:99], v[98:99]
	v_add_f32_e32 v18, v176, v18
	v_add_f32_e32 v18, v178, v18
	v_lshlrev_b32_e32 v140, 16, v144
	v_and_b32_e32 v141, 0xffff0000, v145
	v_add_f32_e32 v18, v179, v18
	v_and_b32_e32 v142, 0xffff0000, v144
	v_lshlrev_b32_e32 v143, 16, v145
	v_pk_mul_f32 v[144:145], v[140:141], v[140:141]
	v_add_f32_e32 v18, v177, v18
	v_pk_mul_f32 v[182:183], v[142:143], v[142:143]
	v_add_f32_e32 v18, v144, v18
	v_add_f32_e32 v18, v182, v18
	s_waitcnt vmcnt(3)
	v_lshlrev_b32_e32 v150, 16, v10
	v_and_b32_e32 v151, 0xffff0000, v11
	v_add_f32_e32 v18, v183, v18
	v_and_b32_e32 v148, 0xffff0000, v10
	v_lshlrev_b32_e32 v149, 16, v11
	v_pk_mul_f32 v[10:11], v[150:151], v[150:151]
	v_add_f32_e32 v18, v145, v18
	v_pk_mul_f32 v[184:185], v[148:149], v[148:149]
	v_add_f32_e32 v10, v10, v18
	v_add_f32_e32 v10, v184, v10
	v_lshlrev_b32_e32 v154, 16, v12
	v_and_b32_e32 v155, 0xffff0000, v13
	v_add_f32_e32 v10, v185, v10
	v_and_b32_e32 v152, 0xffff0000, v12
	v_lshlrev_b32_e32 v153, 16, v13
	v_pk_mul_f32 v[12:13], v[154:155], v[154:155]
	v_add_f32_e32 v10, v11, v10
	v_pk_mul_f32 v[194:195], v[152:153], v[152:153]
	v_add_f32_e32 v10, v12, v10
	v_add_f32_e32 v10, v194, v10
	v_add_f32_e32 v10, v195, v10
	v_add_f32_e32 v10, v13, v10
	v_add_f32_e32 v6, v6, v10
	v_add_f32_e32 v6, v196, v6
	v_add_f32_e32 v6, v197, v6
	v_add_f32_e32 v6, v7, v6
	v_fmac_f32_e32 v6, v134, v134
	v_fmac_f32_e32 v6, v136, v136
	v_add_f32_e32 v6, v9, v6
	v_add_f32_e32 v6, v8, v6
	ds_bpermute_b32 v7, v163, v6
	v_div_scale_f32 v115, s[10:11], v1, v1, v204
	v_rcp_f32_e32 v135, v115
	s_waitcnt vmcnt(1)
	v_and_b32_e32 v108, 0xffff0000, v16
	s_waitcnt lgkmcnt(0)
	v_add_f32_e32 v6, v6, v7
	ds_bpermute_b32 v7, v165, v6
	v_fma_f32 v8, -v115, v135, 1.0
	v_fmac_f32_e32 v135, v8, v135
	v_div_scale_f32 v8, vcc, v204, v1, v204
	s_waitcnt lgkmcnt(0)
	v_add_f32_e32 v6, v6, v7
	ds_bpermute_b32 v7, v166, v6
	v_mul_f32_e32 v9, v8, v135
	v_fma_f32 v10, -v115, v9, v8
	v_fmac_f32_e32 v9, v10, v135
	v_fma_f32 v8, -v115, v9, v8
	s_waitcnt lgkmcnt(0)
	v_add_f32_e32 v82, v6, v7
	ds_bpermute_b32 v83, v167, v82
	v_div_fmas_f32 v8, v8, v135, v9
	v_div_fixup_f32 v1, v8, v1, v204
	v_lshlrev_b32_e32 v112, 16, v16
	v_lshlrev_b32_e32 v109, 16, v17
	s_waitcnt lgkmcnt(0)
	v_add_f32_e32 v88, v82, v83
	ds_bpermute_b32 v89, v168, v88
	v_and_b32_e32 v113, 0xffff0000, v17
	v_and_b32_e32 v80, 0xffff0000, v22
	v_lshlrev_b32_e32 v81, 16, v23
	v_and_b32_e32 v82, 0xffff0000, v24
	s_waitcnt lgkmcnt(0)
	v_add_f32_e32 v88, v88, v89
	ds_bpermute_b32 v89, v169, v88
	v_lshlrev_b32_e32 v83, 16, v25
	v_lshlrev_b32_e32 v22, 16, v22
	v_and_b32_e32 v23, 0xffff0000, v23
	v_lshlrev_b32_e32 v24, 16, v24
	s_waitcnt lgkmcnt(0)
	v_add_f32_e32 v88, v88, v89
	v_fmac_f32_e32 v1, 0x39800000, v88
	v_mul_f32_e32 v88, 0x4f800000, v1
	v_cmp_gt_f32_e32 vcc, s73, v1
	v_and_b32_e32 v25, 0xffff0000, v25
	global_load_dwordx4 v[144:147], v[84:85], off offset:2048 nt
	global_load_dwordx4 v[26:29], v[62:63], off nt
	v_cndmask_b32_e32 v1, v1, v88, vcc
	v_sqrt_f32_e32 v88, v1
	global_load_dwordx4 v[18:21], v[62:63], off offset:1024 nt
	global_load_dwordx4 v[10:13], v[62:63], off offset:2048 nt
	global_load_dwordx4 v[6:9], v[62:63], off offset:3072 nt
	v_and_b32_e32 v104, 0xffff0000, v14
	v_lshlrev_b32_e32 v105, 16, v15
	v_add_u32_e32 v89, -1, v88
	v_fma_f32 v90, -v89, v88, v1
	v_cmp_ge_f32_e64 s[42:43], 0, v90
	v_add_u32_e32 v90, 1, v88
	v_lshlrev_b32_e32 v14, 16, v14
	v_cndmask_b32_e64 v89, v88, v89, s[42:43]
	v_fma_f32 v88, -v90, v88, v1
	v_cmp_lt_f32_e64 s[42:43], 0, v88
	v_and_b32_e32 v15, 0xffff0000, v15
	s_waitcnt vmcnt(4)
	v_lshlrev_b32_e32 v132, 16, v146
	v_cndmask_b32_e64 v88, v89, v90, s[42:43]
	v_mul_f32_e32 v89, 0x37800000, v88
	v_cndmask_b32_e32 v88, v88, v89, vcc
	v_cmp_class_f32_e32 vcc, v1, v205
	v_and_b32_e32 v133, 0xffff0000, v147
	v_and_b32_e32 v122, 0xffff0000, v146
	v_cndmask_b32_e32 v1, v88, v1, vcc
	v_div_scale_f32 v88, s[10:11], v1, v1, 1.0
	v_rcp_f32_e32 v89, v88
	v_lshlrev_b32_e32 v123, 16, v147
	s_waitcnt vmcnt(0)
; #define GAS __attribute__((address_space(1)))
; __device__ __forceinline__ void unpack8(v4u w, float (&f)[8]) { f[0] = bflo(w.x); f[1] = bfhi(w.x); f[2] = bflo(w.y); f[3] = bfhi(w.y); f[4] = bflo(w.z); f[5] = bfhi(w.z); f[6] = bflo(w.w); f[7] = bfhi(w.w); }
; __device__ __forceinline__ v4u pack8(const float (&o)[8]) { v4u w; w.x = pk2(o[0], o[1]); w.y = pk2(o[2], o[3]); w.z = pk2(o[4], o[5]); w.w = pk2(o[6], o[7]); return w; }
; template <bool XF32, bool FINAL, bool QUANT = false> ...
;     ...
;     for (int j = 0; j < 8; ++j) { const int c = 8 * lane + 512 * j; float yf[8], x[8]; unpack8(yraw[j], yf);
;         if (XF32) { x[0] = xf[j][0].x; x[1] = xf[j][0].y; x[2] = xf[j][0].z; x[3] = xf[j][0].w; x[4] = xf[j][1].x; x[5] = xf[j][1].y; x[6] = xf[j][1].z; x[7] = xf[j][1].w; }
;         else unpack8(xr[j], x);
;         const f32x4 g0 = *(const GAS f32x4*)(gpost + c), g1 = *(const GAS f32x4*)(gpost + c + 4);
; #pragma unroll
;         for (int e = 0; e < 4; ++e) { x[e] += yf[e] * rstd * g0[e]; x[4 + e] += yf[4 + e] * rstd * g1[e]; }
;         if (FINAL) { *(GAS f32x4*)(orow + c) = (f32x4){x[0], x[1], x[2], x[3]}; *(GAS f32x4*)(orow + c + 4) = (f32x4){x[4], x[5], x[6], x[7]}; }
;         else {
; #pragma unroll
;             for (int e = 0; e < 8; ++e) s2 += x[e] * x[e];
;             const v4u pw = pack8(x); *(GAS v4u*)(xbrow + c) = pw;
;             if (QUANT) { xr[j] = pw;
; #pragma unroll
;                 for (int e = 0; e < 8; ++e) am = fmaxf(am, fabsf(x[e])); } }
;         if (j & 1) asm volatile("" ::: "memory"); }
	v_lshlrev_b32_e32 v194, 16, v6
	v_and_b32_e32 v195, 0xffff0000, v7
	v_fma_f32 v16, -v88, v89, 1.0
	v_fmac_f32_e32 v89, v16, v89
	v_div_scale_f32 v16, vcc, 1.0, v1, 1.0
	v_mul_f32_e32 v17, v16, v89
	v_fma_f32 v90, -v88, v17, v16
	v_fmac_f32_e32 v17, v90, v89
	v_fma_f32 v16, -v88, v17, v16
	v_div_fmas_f32 v16, v16, v89, v17
	v_div_fixup_f32 v160, v16, v1, 1.0
	v_pk_mul_f32 v[16:17], v[160:161], v[70:71] op_sel_hi:[0,1]
	v_pk_fma_f32 v[88:89], v[44:45], v[16:17], v[80:81]
	v_pk_mul_f32 v[16:17], v[160:161], v[78:79] op_sel_hi:[0,1]
	v_pk_fma_f32 v[90:91], v[48:49], v[16:17], v[82:83]
	v_pk_mul_f32 v[16:17], v[160:161], v[66:67] op_sel_hi:[0,1]
	v_pk_fma_f32 v[92:93], v[42:43], v[16:17], v[22:23]
	v_pk_mul_f32 v[16:17], v[160:161], v[72:73] op_sel_hi:[0,1]
	v_pk_fma_f32 v[94:95], v[46:47], v[16:17], v[24:25]
	v_and_b32_sdwa v1, v89, v203 dst_sel:DWORD dst_unused:UNUSED_PAD src0_sel:WORD_1 src1_sel:DWORD
	v_and_b32_sdwa v16, v88, v203 dst_sel:DWORD dst_unused:UNUSED_PAD src0_sel:WORD_1 src1_sel:DWORD
	v_add3_u32 v79, v89, v1, s14
	v_add3_u32 v1, v88, v16, s14
	v_and_b32_e32 v72, 0xffff0000, v1
	v_and_b32_sdwa v1, v93, v203 dst_sel:DWORD dst_unused:UNUSED_PAD src0_sel:WORD_1 src1_sel:DWORD
	v_and_b32_sdwa v16, v92, v203 dst_sel:DWORD dst_unused:UNUSED_PAD src0_sel:WORD_1 src1_sel:DWORD
	v_add3_u32 v1, v93, v1, s14
	v_add3_u32 v80, v92, v16, s14
	v_and_b32_e32 v71, 0xffff0000, v1
	v_and_b32_sdwa v1, v91, v203 dst_sel:DWORD dst_unused:UNUSED_PAD src0_sel:WORD_1 src1_sel:DWORD
	v_and_b32_sdwa v16, v90, v203 dst_sel:DWORD dst_unused:UNUSED_PAD src0_sel:WORD_1 src1_sel:DWORD
	v_add3_u32 v81, v91, v1, s14
	v_add3_u32 v1, v90, v16, s14
	v_and_b32_e32 v66, 0xffff0000, v1
	v_and_b32_sdwa v1, v95, v203 dst_sel:DWORD dst_unused:UNUSED_PAD src0_sel:WORD_1 src1_sel:DWORD
	v_and_b32_sdwa v16, v94, v203 dst_sel:DWORD dst_unused:UNUSED_PAD src0_sel:WORD_1 src1_sel:DWORD
	v_add3_u32 v1, v95, v1, s14
	v_add3_u32 v82, v94, v16, s14
	v_and_b32_e32 v17, 0xffff0000, v1
	v_or_b32_sdwa v23, v71, v79 dst_sel:DWORD dst_unused:UNUSED_PAD src0_sel:DWORD src1_sel:WORD_1
	v_or_b32_sdwa v22, v80, v72 dst_sel:DWORD dst_unused:UNUSED_PAD src0_sel:WORD_1 src1_sel:DWORD
	v_or_b32_sdwa v25, v17, v81 dst_sel:DWORD dst_unused:UNUSED_PAD src0_sel:DWORD src1_sel:WORD_1
	v_or_b32_sdwa v24, v82, v66 dst_sel:DWORD dst_unused:UNUSED_PAD src0_sel:WORD_1 src1_sel:DWORD
	global_store_dwordx4 v[62:63], v[22:25], off offset:-4096
	v_pk_mul_f32 v[74:75], v[160:161], v[74:75] op_sel_hi:[0,1]
	v_pk_mul_f32 v[64:65], v[160:161], v[64:65] op_sel_hi:[0,1]
	v_pk_mul_f32 v[22:23], v[160:161], v[100:101] op_sel_hi:[0,1]
	v_pk_fma_f32 v[100:101], v[52:53], v[22:23], v[104:105]
	v_pk_mul_f32 v[22:23], v[160:161], v[102:103] op_sel_hi:[0,1]
	v_pk_fma_f32 v[102:103], v[56:57], v[22:23], v[108:109]
	v_pk_mul_f32 v[22:23], v[160:161], v[68:69] op_sel_hi:[0,1]
	v_pk_fma_f32 v[104:105], v[50:51], v[22:23], v[14:15]
	v_pk_mul_f32 v[14:15], v[160:161], v[106:107] op_sel_hi:[0,1]
	v_pk_fma_f32 v[106:107], v[54:55], v[14:15], v[112:113]
	v_and_b32_sdwa v1, v101, v203 dst_sel:DWORD dst_unused:UNUSED_PAD src0_sel:WORD_1 src1_sel:DWORD
	v_and_b32_sdwa v14, v100, v203 dst_sel:DWORD dst_unused:UNUSED_PAD src0_sel:WORD_1 src1_sel:DWORD
	v_add3_u32 v23, v101, v1, s14
	v_add3_u32 v1, v100, v14, s14
	v_and_b32_e32 v16, 0xffff0000, v1
	v_and_b32_sdwa v1, v105, v203 dst_sel:DWORD dst_unused:UNUSED_PAD src0_sel:WORD_1 src1_sel:DWORD
	v_and_b32_sdwa v14, v104, v203 dst_sel:DWORD dst_unused:UNUSED_PAD src0_sel:WORD_1 src1_sel:DWORD
	v_add3_u32 v1, v105, v1, s14
	v_add3_u32 v24, v104, v14, s14
	v_and_b32_e32 v15, 0xffff0000, v1
	v_and_b32_sdwa v1, v103, v203 dst_sel:DWORD dst_unused:UNUSED_PAD src0_sel:WORD_1 src1_sel:DWORD
	v_and_b32_sdwa v14, v102, v203 dst_sel:DWORD dst_unused:UNUSED_PAD src0_sel:WORD_1 src1_sel:DWORD
	v_add3_u32 v67, v103, v1, s14
	v_add3_u32 v1, v102, v14, s14
	v_and_b32_e32 v14, 0xffff0000, v1
	v_and_b32_sdwa v1, v107, v203 dst_sel:DWORD dst_unused:UNUSED_PAD src0_sel:WORD_1 src1_sel:DWORD
	v_and_b32_sdwa v22, v106, v203 dst_sel:DWORD dst_unused:UNUSED_PAD src0_sel:WORD_1 src1_sel:DWORD
	v_add3_u32 v1, v107, v1, s14
	v_add3_u32 v68, v106, v22, s14
	v_and_b32_e32 v1, 0xffff0000, v1
	v_or_b32_sdwa v171, v15, v23 dst_sel:DWORD dst_unused:UNUSED_PAD src0_sel:DWORD src1_sel:WORD_1
	v_or_b32_sdwa v170, v24, v16 dst_sel:DWORD dst_unused:UNUSED_PAD src0_sel:WORD_1 src1_sel:DWORD
	v_or_b32_sdwa v173, v1, v67 dst_sel:DWORD dst_unused:UNUSED_PAD src0_sel:DWORD src1_sel:WORD_1
	v_or_b32_sdwa v172, v68, v14 dst_sel:DWORD dst_unused:UNUSED_PAD src0_sel:WORD_1 src1_sel:DWORD
	global_store_dwordx4 v[84:85], v[170:173], off offset:1024
	global_load_dwordx4 v[170:173], v[30:31], off
	global_load_dwordx4 v[174:177], v[30:31], off offset:16
	v_and_b32_e32 v108, 0xffff0000, v144
	v_lshlrev_b32_e32 v109, 16, v145
	v_lshlrev_b32_e32 v112, 16, v144
	v_and_b32_e32 v113, 0xffff0000, v145
	v_pk_mul_f32 v[118:119], v[160:161], v[118:119] op_sel_hi:[0,1]
	v_pk_mul_f32 v[120:121], v[160:161], v[120:121] op_sel_hi:[0,1]
	v_pk_mul_f32 v[76:77], v[160:161], v[76:77] op_sel_hi:[0,1]
	v_pk_mul_f32 v[126:127], v[160:161], v[126:127] op_sel_hi:[0,1]
	v_pk_mul_f32 v[130:131], v[160:161], v[130:131] op_sel_hi:[0,1]
	v_pk_mul_f32 v[86:87], v[160:161], v[86:87] op_sel_hi:[0,1]
	v_pk_mul_f32 v[98:99], v[160:161], v[98:99] op_sel_hi:[0,1]
	v_pk_mul_f32 v[178:179], v[160:161], v[142:143] op_sel_hi:[0,1]
	v_pk_mul_f32 v[96:97], v[160:161], v[96:97] op_sel_hi:[0,1]
	v_pk_mul_f32 v[182:183], v[160:161], v[140:141] op_sel_hi:[0,1]
	v_and_b32_e32 v196, 0xffff0000, v8
	v_lshlrev_b32_e32 v197, 16, v9
	v_lshlrev_b32_e32 v198, 16, v8
	v_and_b32_e32 v199, 0xffff0000, v9
	v_pk_mul_f32 v[8:9], v[160:161], v[152:153] op_sel_hi:[0,1]
	v_pk_mul_f32 v[200:201], v[160:161], v[156:157] op_sel_hi:[0,1]
	v_pk_mul_f32 v[214:215], v[160:161], v[158:159] op_sel_hi:[0,1]
	v_pk_mul_f32 v[216:217], v[160:161], v[136:137] op_sel_hi:[0,1]
	v_pk_mul_f32 v[218:219], v[92:93], v[92:93]
	v_pk_mul_f32 v[220:221], v[88:89], v[88:89]
	v_pk_mul_f32 v[222:223], v[94:95], v[94:95]
	v_pk_mul_f32 v[224:225], v[90:91], v[90:91]
	s_add_u32 s10, s8, 0x130000
	s_addc_u32 s11, s9, 0
	s_waitcnt vmcnt(1)
; #define GAS __attribute__((address_space(1)))
; __device__ __forceinline__ void unpack8(v4u w, float (&f)[8]) { f[0] = bflo(w.x); f[1] = bfhi(w.x); f[2] = bflo(w.y); f[3] = bfhi(w.y); f[4] = bflo(w.z); f[5] = bfhi(w.z); f[6] = bflo(w.w); f[7] = bfhi(w.w); }
; __device__ __forceinline__ v4u pack8(const float (&o)[8]) { v4u w; w.x = pk2(o[0], o[1]); w.y = pk2(o[2], o[3]); w.z = pk2(o[4], o[5]); w.w = pk2(o[6], o[7]); return w; }
; template <bool XF32, bool FINAL, bool QUANT = false> ...
;     ...
;     for (int j = 0; j < 8; ++j) { const int c = 8 * lane + 512 * j; float yf[8], x[8]; unpack8(yraw[j], yf);
;         if (XF32) { x[0] = xf[j][0].x; x[1] = xf[j][0].y; x[2] = xf[j][0].z; x[3] = xf[j][0].w; x[4] = xf[j][1].x; x[5] = xf[j][1].y; x[6] = xf[j][1].z; x[7] = xf[j][1].w; }
;         else unpack8(xr[j], x);
;         const f32x4 g0 = *(const GAS f32x4*)(gpost + c), g1 = *(const GAS f32x4*)(gpost + c + 4);
; #pragma unroll
;         for (int e = 0; e < 4; ++e) { x[e] += yf[e] * rstd * g0[e]; x[4 + e] += yf[4 + e] * rstd * g1[e]; }
;         if (FINAL) { *(GAS f32x4*)(orow + c) = (f32x4){x[0], x[1], x[2], x[3]}; *(GAS f32x4*)(orow + c + 4) = (f32x4){x[4], x[5], x[6], x[7]}; }
;         else {
; #pragma unroll
;             for (int e = 0; e < 8; ++e) s2 += x[e] * x[e];
;             const v4u pw = pack8(x); *(GAS v4u*)(xbrow + c) = pw;
;             if (QUANT) { xr[j] = pw;
; #pragma unroll
;                 for (int e = 0; e < 8; ++e) am = fmaxf(am, fabsf(x[e])); } }
;         if (j & 1) asm volatile("" ::: "memory"); }
	v_mov_b32_e32 v144, v171
	v_mov_b32_e32 v145, v172
	v_pk_fma_f32 v[108:109], v[144:145], v[74:75], v[108:109]
	v_mov_b32_e32 v171, v173
	v_and_b32_sdwa v22, v109, v203 dst_sel:DWORD dst_unused:UNUSED_PAD src0_sel:WORD_1 src1_sel:DWORD
	v_and_b32_sdwa v25, v108, v203 dst_sel:DWORD dst_unused:UNUSED_PAD src0_sel:WORD_1 src1_sel:DWORD
	v_pk_mul_f32 v[74:75], v[160:161], v[110:111] op_sel_hi:[0,1]
	s_waitcnt vmcnt(0)
	v_mov_b32_e32 v110, v175
	v_pk_fma_f32 v[112:113], v[170:171], v[64:65], v[112:113]
	v_pk_mul_f32 v[64:65], v[160:161], v[116:117] op_sel_hi:[0,1]
	v_mov_b32_e32 v175, v177
	v_add3_u32 v69, v109, v22, s14
	v_add3_u32 v22, v108, v25, s14
	v_mov_b32_e32 v111, v176
	v_pk_fma_f32 v[116:117], v[174:175], v[64:65], v[132:133]
	v_and_b32_e32 v64, 0xffff0000, v22
	v_and_b32_sdwa v22, v113, v203 dst_sel:DWORD dst_unused:UNUSED_PAD src0_sel:WORD_1 src1_sel:DWORD
	v_pk_fma_f32 v[110:111], v[110:111], v[74:75], v[122:123]
	v_and_b32_sdwa v25, v112, v203 dst_sel:DWORD dst_unused:UNUSED_PAD src0_sel:WORD_1 src1_sel:DWORD
	v_add3_u32 v22, v113, v22, s14
	v_add3_u32 v70, v112, v25, s14
	v_and_b32_e32 v65, 0xffff0000, v22
	v_and_b32_sdwa v22, v111, v203 dst_sel:DWORD dst_unused:UNUSED_PAD src0_sel:WORD_1 src1_sel:DWORD
	v_and_b32_sdwa v25, v110, v203 dst_sel:DWORD dst_unused:UNUSED_PAD src0_sel:WORD_1 src1_sel:DWORD
	v_add3_u32 v73, v111, v22, s14
	v_add3_u32 v22, v110, v25, s14
	v_and_b32_sdwa v25, v117, v203 dst_sel:DWORD dst_unused:UNUSED_PAD src0_sel:WORD_1 src1_sel:DWORD
	v_and_b32_sdwa v74, v116, v203 dst_sel:DWORD dst_unused:UNUSED_PAD src0_sel:WORD_1 src1_sel:DWORD
	v_add3_u32 v25, v117, v25, s14
	v_and_b32_e32 v22, 0xffff0000, v22
	v_add3_u32 v74, v116, v74, s14
	v_and_b32_e32 v25, 0xffff0000, v25
	v_or_b32_sdwa v145, v65, v69 dst_sel:DWORD dst_unused:UNUSED_PAD src0_sel:DWORD src1_sel:WORD_1
	v_or_b32_sdwa v144, v70, v64 dst_sel:DWORD dst_unused:UNUSED_PAD src0_sel:WORD_1 src1_sel:DWORD
	v_or_b32_sdwa v147, v25, v73 dst_sel:DWORD dst_unused:UNUSED_PAD src0_sel:DWORD src1_sel:WORD_1
	v_or_b32_sdwa v146, v74, v22 dst_sel:DWORD dst_unused:UNUSED_PAD src0_sel:WORD_1 src1_sel:DWORD
	global_store_dwordx4 v[84:85], v[144:147], off offset:2048
	global_load_dwordx4 v[144:147], v[32:33], off
	s_nop 0
	global_load_dwordx4 v[170:173], v[32:33], off offset:16
	v_and_b32_e32 v122, 0xffff0000, v2
	v_lshlrev_b32_e32 v123, 16, v3
	v_lshlrev_b32_e32 v2, 16, v2
	v_and_b32_e32 v3, 0xffff0000, v3
	v_and_b32_e32 v132, 0xffff0000, v4
	v_lshlrev_b32_e32 v133, 16, v5
	v_lshlrev_b32_e32 v4, 16, v4
	v_and_b32_e32 v5, 0xffff0000, v5
	s_waitcnt vmcnt(1)
	v_mov_b32_e32 v174, v145
	v_mov_b32_e32 v175, v146
	v_pk_fma_f32 v[118:119], v[174:175], v[118:119], v[122:123]
	s_waitcnt vmcnt(0)
	v_mov_b32_e32 v122, v171
	v_mov_b32_e32 v123, v172
	v_mov_b32_e32 v145, v147
	v_pk_fma_f32 v[120:121], v[122:123], v[120:121], v[132:133]
	v_pk_fma_f32 v[122:123], v[144:145], v[76:77], v[2:3]
	v_pk_mul_f32 v[2:3], v[160:161], v[124:125] op_sel_hi:[0,1]
	v_mov_b32_e32 v171, v173
	v_pk_fma_f32 v[124:125], v[170:171], v[2:3], v[4:5]
	v_and_b32_sdwa v2, v119, v203 dst_sel:DWORD dst_unused:UNUSED_PAD src0_sel:WORD_1 src1_sel:DWORD
	v_and_b32_sdwa v3, v118, v203 dst_sel:DWORD dst_unused:UNUSED_PAD src0_sel:WORD_1 src1_sel:DWORD
	v_add3_u32 v75, v119, v2, s14
	v_add3_u32 v2, v118, v3, s14
	v_and_b32_e32 v4, 0xffff0000, v2
	v_and_b32_sdwa v2, v123, v203 dst_sel:DWORD dst_unused:UNUSED_PAD src0_sel:WORD_1 src1_sel:DWORD
	v_and_b32_sdwa v3, v122, v203 dst_sel:DWORD dst_unused:UNUSED_PAD src0_sel:WORD_1 src1_sel:DWORD
	v_add3_u32 v2, v123, v2, s14
	v_add3_u32 v76, v122, v3, s14
	v_and_b32_e32 v5, 0xffff0000, v2
	v_and_b32_sdwa v2, v121, v203 dst_sel:DWORD dst_unused:UNUSED_PAD src0_sel:WORD_1 src1_sel:DWORD
	v_and_b32_sdwa v3, v120, v203 dst_sel:DWORD dst_unused:UNUSED_PAD src0_sel:WORD_1 src1_sel:DWORD
	v_add3_u32 v77, v121, v2, s14
	v_add3_u32 v2, v120, v3, s14
	v_and_b32_sdwa v3, v125, v203 dst_sel:DWORD dst_unused:UNUSED_PAD src0_sel:WORD_1 src1_sel:DWORD
	v_and_b32_sdwa v78, v124, v203 dst_sel:DWORD dst_unused:UNUSED_PAD src0_sel:WORD_1 src1_sel:DWORD
	v_add3_u32 v3, v125, v3, s14
	v_and_b32_e32 v2, 0xffff0000, v2
	v_add3_u32 v78, v124, v78, s14
	v_and_b32_e32 v3, 0xffff0000, v3
	v_or_b32_sdwa v145, v5, v75 dst_sel:DWORD dst_unused:UNUSED_PAD src0_sel:DWORD src1_sel:WORD_1
	v_or_b32_sdwa v144, v76, v4 dst_sel:DWORD dst_unused:UNUSED_PAD src0_sel:WORD_1 src1_sel:DWORD
	v_or_b32_sdwa v147, v3, v77 dst_sel:DWORD dst_unused:UNUSED_PAD src0_sel:DWORD src1_sel:WORD_1
	v_or_b32_sdwa v146, v78, v2 dst_sel:DWORD dst_unused:UNUSED_PAD src0_sel:WORD_1 src1_sel:DWORD
	global_store_dwordx4 v[84:85], v[144:147], off offset:3072
	global_load_dwordx4 v[144:147], v[34:35], off
	global_load_dwordx4 v[170:173], v[34:35], off offset:16
	v_and_b32_e32 v84, 0xffff0000, v26
	v_lshlrev_b32_e32 v85, 16, v27
	v_lshlrev_b32_e32 v26, 16, v26
	v_and_b32_e32 v27, 0xffff0000, v27
	v_and_b32_e32 v132, 0xffff0000, v28
	v_lshlrev_b32_e32 v133, 16, v29
	v_pk_mul_f32 v[174:175], v[160:161], v[128:129] op_sel_hi:[0,1]
	v_lshlrev_b32_e32 v28, 16, v28
	v_and_b32_e32 v29, 0xffff0000, v29
	s_waitcnt vmcnt(1)
	v_mov_b32_e32 v128, v145
	v_mov_b32_e32 v129, v146
	s_waitcnt vmcnt(0)
; #define GAS __attribute__((address_space(1)))
; __device__ __forceinline__ void unpack8(v4u w, float (&f)[8]) { f[0] = bflo(w.x); f[1] = bfhi(w.x); f[2] = bflo(w.y); f[3] = bfhi(w.y); f[4] = bflo(w.z); f[5] = bfhi(w.z); f[6] = bflo(w.w); f[7] = bfhi(w.w); }
; __device__ __forceinline__ v4u pack8(const float (&o)[8]) { v4u w; w.x = pk2(o[0], o[1]); w.y = pk2(o[2], o[3]); w.z = pk2(o[4], o[5]); w.w = pk2(o[6], o[7]); return w; }
; template <bool XF32, bool FINAL, bool QUANT = false> ...
;     ...
;     for (int j = 0; j < 8; ++j) { const int c = 8 * lane + 512 * j; float yf[8], x[8]; unpack8(yraw[j], yf);
;         if (XF32) { x[0] = xf[j][0].x; x[1] = xf[j][0].y; x[2] = xf[j][0].z; x[3] = xf[j][0].w; x[4] = xf[j][1].x; x[5] = xf[j][1].y; x[6] = xf[j][1].z; x[7] = xf[j][1].w; }
;         else unpack8(xr[j], x);
;         const f32x4 g0 = *(const GAS f32x4*)(gpost + c), g1 = *(const GAS f32x4*)(gpost + c + 4);
; #pragma unroll
;         for (int e = 0; e < 4; ++e) { x[e] += yf[e] * rstd * g0[e]; x[4 + e] += yf[4 + e] * rstd * g1[e]; }
;         if (FINAL) { *(GAS f32x4*)(orow + c) = (f32x4){x[0], x[1], x[2], x[3]}; *(GAS f32x4*)(orow + c + 4) = (f32x4){x[4], x[5], x[6], x[7]}; }
;         else {
; #pragma unroll
;             for (int e = 0; e < 8; ++e) s2 += x[e] * x[e];
;             const v4u pw = pack8(x); *(GAS v4u*)(xbrow + c) = pw;
;             if (QUANT) { xr[j] = pw;
; #pragma unroll
;                 for (int e = 0; e < 8; ++e) am = fmaxf(am, fabsf(x[e])); } }
;         if (j & 1) asm volatile("" ::: "memory"); }
	v_mov_b32_e32 v176, v171
	v_mov_b32_e32 v177, v172
	v_mov_b32_e32 v145, v147
	v_mov_b32_e32 v171, v173
	v_pk_fma_f32 v[128:129], v[128:129], v[126:127], v[84:85]
	v_pk_fma_f32 v[126:127], v[176:177], v[130:131], v[132:133]
	v_pk_fma_f32 v[132:133], v[144:145], v[86:87], v[26:27]
	v_pk_fma_f32 v[130:131], v[170:171], v[174:175], v[28:29]
	v_and_b32_sdwa v26, v129, v203 dst_sel:DWORD dst_unused:UNUSED_PAD src0_sel:WORD_1 src1_sel:DWORD
	v_and_b32_sdwa v27, v128, v203 dst_sel:DWORD dst_unused:UNUSED_PAD src0_sel:WORD_1 src1_sel:DWORD
	v_and_b32_sdwa v28, v133, v203 dst_sel:DWORD dst_unused:UNUSED_PAD src0_sel:WORD_1 src1_sel:DWORD
	v_and_b32_sdwa v29, v132, v203 dst_sel:DWORD dst_unused:UNUSED_PAD src0_sel:WORD_1 src1_sel:DWORD
	v_add3_u32 v83, v129, v26, s14
	v_add3_u32 v26, v128, v27, s14
	v_add3_u32 v27, v133, v28, s14
	v_and_b32_sdwa v86, v126, v203 dst_sel:DWORD dst_unused:UNUSED_PAD src0_sel:WORD_1 src1_sel:DWORD
	v_add3_u32 v84, v132, v29, s14
	v_and_b32_e32 v29, 0xffff0000, v27
	v_and_b32_sdwa v27, v131, v203 dst_sel:DWORD dst_unused:UNUSED_PAD src0_sel:WORD_1 src1_sel:DWORD
	v_and_b32_sdwa v85, v127, v203 dst_sel:DWORD dst_unused:UNUSED_PAD src0_sel:WORD_1 src1_sel:DWORD
	v_and_b32_e32 v28, 0xffff0000, v26
	v_add3_u32 v26, v126, v86, s14
	v_and_b32_sdwa v86, v130, v203 dst_sel:DWORD dst_unused:UNUSED_PAD src0_sel:WORD_1 src1_sel:DWORD
	v_add3_u32 v27, v131, v27, s14
	v_add3_u32 v85, v127, v85, s14
	v_and_b32_e32 v26, 0xffff0000, v26
	v_add3_u32 v86, v130, v86, s14
	v_and_b32_e32 v27, 0xffff0000, v27
	v_or_b32_sdwa v145, v29, v83 dst_sel:DWORD dst_unused:UNUSED_PAD src0_sel:DWORD src1_sel:WORD_1
	v_or_b32_sdwa v144, v84, v28 dst_sel:DWORD dst_unused:UNUSED_PAD src0_sel:WORD_1 src1_sel:DWORD
	v_or_b32_sdwa v147, v27, v85 dst_sel:DWORD dst_unused:UNUSED_PAD src0_sel:DWORD src1_sel:WORD_1
	v_or_b32_sdwa v146, v86, v26 dst_sel:DWORD dst_unused:UNUSED_PAD src0_sel:WORD_1 src1_sel:DWORD
	global_store_dwordx4 v[62:63], v[144:147], off
	global_load_dwordx4 v[144:147], v[36:37], off
	s_nop 0
	global_load_dwordx4 v[170:173], v[36:37], off offset:16
	v_and_b32_e32 v174, 0xffff0000, v18
	v_lshlrev_b32_e32 v175, 16, v19
	v_lshlrev_b32_e32 v18, 16, v18
	v_and_b32_e32 v19, 0xffff0000, v19
	v_and_b32_e32 v176, 0xffff0000, v20
	v_lshlrev_b32_e32 v177, 16, v21
	v_lshlrev_b32_e32 v20, 16, v20
	v_and_b32_e32 v21, 0xffff0000, v21
	s_waitcnt vmcnt(1)
	v_mov_b32_e32 v140, v145
	v_mov_b32_e32 v141, v146
	s_waitcnt vmcnt(0)
	v_mov_b32_e32 v184, v171
	v_mov_b32_e32 v185, v172
	v_mov_b32_e32 v145, v147
	v_mov_b32_e32 v171, v173
	v_pk_fma_f32 v[142:143], v[140:141], v[98:99], v[174:175]
	v_pk_fma_f32 v[140:141], v[184:185], v[178:179], v[176:177]
	v_pk_fma_f32 v[146:147], v[144:145], v[96:97], v[18:19]
	v_pk_fma_f32 v[144:145], v[170:171], v[182:183], v[20:21]
	v_and_b32_sdwa v18, v143, v203 dst_sel:DWORD dst_unused:UNUSED_PAD src0_sel:WORD_1 src1_sel:DWORD
	v_and_b32_sdwa v19, v142, v203 dst_sel:DWORD dst_unused:UNUSED_PAD src0_sel:WORD_1 src1_sel:DWORD
	v_and_b32_sdwa v20, v147, v203 dst_sel:DWORD dst_unused:UNUSED_PAD src0_sel:WORD_1 src1_sel:DWORD
	v_and_b32_sdwa v98, v140, v203 dst_sel:DWORD dst_unused:UNUSED_PAD src0_sel:WORD_1 src1_sel:DWORD
	v_and_b32_sdwa v99, v145, v203 dst_sel:DWORD dst_unused:UNUSED_PAD src0_sel:WORD_1 src1_sel:DWORD
	v_and_b32_sdwa v21, v146, v203 dst_sel:DWORD dst_unused:UNUSED_PAD src0_sel:WORD_1 src1_sel:DWORD
	v_and_b32_sdwa v97, v141, v203 dst_sel:DWORD dst_unused:UNUSED_PAD src0_sel:WORD_1 src1_sel:DWORD
	v_and_b32_sdwa v115, v144, v203 dst_sel:DWORD dst_unused:UNUSED_PAD src0_sel:WORD_1 src1_sel:DWORD
	v_add3_u32 v87, v143, v18, s14
	v_add3_u32 v18, v142, v19, s14
	v_add3_u32 v19, v147, v20, s14
	v_add3_u32 v135, v140, v98, s14
	v_add3_u32 v99, v145, v99, s14
	v_add3_u32 v96, v146, v21, s14
	v_add3_u32 v97, v141, v97, s14
	v_add3_u32 v98, v144, v115, s14
	v_and_b32_e32 v20, 0xffff0000, v18
	v_and_b32_e32 v21, 0xffff0000, v19
	v_and_b32_e32 v18, 0xffff0000, v135
	v_and_b32_e32 v19, 0xffff0000, v99
	v_or_b32_sdwa v171, v21, v87 dst_sel:DWORD dst_unused:UNUSED_PAD src0_sel:DWORD src1_sel:WORD_1
	v_or_b32_sdwa v170, v96, v20 dst_sel:DWORD dst_unused:UNUSED_PAD src0_sel:WORD_1 src1_sel:DWORD
	v_or_b32_sdwa v173, v19, v97 dst_sel:DWORD dst_unused:UNUSED_PAD src0_sel:DWORD src1_sel:WORD_1
	v_or_b32_sdwa v172, v98, v18 dst_sel:DWORD dst_unused:UNUSED_PAD src0_sel:WORD_1 src1_sel:DWORD
	global_store_dwordx4 v[62:63], v[170:173], off offset:1024
	global_load_dwordx4 v[170:173], v[38:39], off
	global_load_dwordx4 v[174:177], v[38:39], off offset:16
	v_mov_b32_e32 v135, v138
	v_and_b32_e32 v178, 0xffff0000, v10
	v_lshlrev_b32_e32 v179, 16, v11
	v_lshlrev_b32_e32 v10, 16, v10
	v_and_b32_e32 v11, 0xffff0000, v11
	v_and_b32_e32 v182, 0xffff0000, v12
	v_lshlrev_b32_e32 v183, 16, v13
	v_lshlrev_b32_e32 v12, 16, v12
	v_and_b32_e32 v13, 0xffff0000, v13
	v_and_b32_e32 v184, 0xffff0000, v6
	v_lshlrev_b32_e32 v185, 16, v7
	v_pk_mul_f32 v[6:7], v[160:161], v[148:149] op_sel_hi:[0,1]
	v_pk_mul_f32 v[138:139], v[160:161], v[150:151] op_sel_hi:[0,1]
	v_pk_mul_f32 v[150:151], v[160:161], v[154:155] op_sel_hi:[0,1]
	v_pk_mul_f32 v[160:161], v[160:161], v[134:135] op_sel_hi:[0,1]
	s_waitcnt vmcnt(1)
	v_mov_b32_e32 v134, v171
	v_mov_b32_e32 v135, v172
	s_waitcnt vmcnt(0)
; #define GAS __attribute__((address_space(1)))
; __device__ __forceinline__ void unpack8(v4u w, float (&f)[8]) { f[0] = bflo(w.x); f[1] = bfhi(w.x); f[2] = bflo(w.y); f[3] = bfhi(w.y); f[4] = bflo(w.z); f[5] = bfhi(w.z); f[6] = bflo(w.w); f[7] = bfhi(w.w); }
; __device__ __forceinline__ v4u pack8(const float (&o)[8]) { v4u w; w.x = pk2(o[0], o[1]); w.y = pk2(o[2], o[3]); w.z = pk2(o[4], o[5]); w.w = pk2(o[6], o[7]); return w; }
; template <bool XF32, bool FINAL, bool QUANT = false> ...
;     ...
;     for (int j = 0; j < 8; ++j) { const int c = 8 * lane + 512 * j; float yf[8], x[8]; unpack8(yraw[j], yf);
;         if (XF32) { x[0] = xf[j][0].x; x[1] = xf[j][0].y; x[2] = xf[j][0].z; x[3] = xf[j][0].w; x[4] = xf[j][1].x; x[5] = xf[j][1].y; x[6] = xf[j][1].z; x[7] = xf[j][1].w; }
;         else unpack8(xr[j], x);
;         const f32x4 g0 = *(const GAS f32x4*)(gpost + c), g1 = *(const GAS f32x4*)(gpost + c + 4);
; #pragma unroll
;         for (int e = 0; e < 4; ++e) { x[e] += yf[e] * rstd * g0[e]; x[4 + e] += yf[4 + e] * rstd * g1[e]; }
;         if (FINAL) { *(GAS f32x4*)(orow + c) = (f32x4){x[0], x[1], x[2], x[3]}; *(GAS f32x4*)(orow + c + 4) = (f32x4){x[4], x[5], x[6], x[7]}; }
;         else {
; #pragma unroll
;             for (int e = 0; e < 8; ++e) s2 += x[e] * x[e];
;             const v4u pw = pack8(x); *(GAS v4u*)(xbrow + c) = pw;
;             if (QUANT) { xr[j] = pw;
; #pragma unroll
;                 for (int e = 0; e < 8; ++e) am = fmaxf(am, fabsf(x[e])); } }
;         if (j & 1) asm volatile("" ::: "memory"); }
	v_mov_b32_e32 v148, v175
	v_mov_b32_e32 v149, v176
	v_mov_b32_e32 v171, v173
	v_mov_b32_e32 v175, v177
	v_pk_fma_f32 v[136:137], v[134:135], v[6:7], v[178:179]
	v_pk_fma_f32 v[134:135], v[148:149], v[8:9], v[182:183]
	v_pk_fma_f32 v[148:149], v[170:171], v[138:139], v[10:11]
	v_pk_fma_f32 v[138:139], v[174:175], v[150:151], v[12:13]
	v_and_b32_sdwa v6, v137, v203 dst_sel:DWORD dst_unused:UNUSED_PAD src0_sel:WORD_1 src1_sel:DWORD
	v_and_b32_sdwa v7, v136, v203 dst_sel:DWORD dst_unused:UNUSED_PAD src0_sel:WORD_1 src1_sel:DWORD
	v_and_b32_sdwa v8, v149, v203 dst_sel:DWORD dst_unused:UNUSED_PAD src0_sel:WORD_1 src1_sel:DWORD
	v_and_b32_sdwa v99, v134, v203 dst_sel:DWORD dst_unused:UNUSED_PAD src0_sel:WORD_1 src1_sel:DWORD
	v_and_b32_sdwa v115, v139, v203 dst_sel:DWORD dst_unused:UNUSED_PAD src0_sel:WORD_1 src1_sel:DWORD
	v_and_b32_sdwa v9, v148, v203 dst_sel:DWORD dst_unused:UNUSED_PAD src0_sel:WORD_1 src1_sel:DWORD
	v_and_b32_sdwa v12, v135, v203 dst_sel:DWORD dst_unused:UNUSED_PAD src0_sel:WORD_1 src1_sel:DWORD
	v_and_b32_sdwa v150, v138, v203 dst_sel:DWORD dst_unused:UNUSED_PAD src0_sel:WORD_1 src1_sel:DWORD
	v_add3_u32 v11, v137, v6, s14
	v_add3_u32 v6, v136, v7, s14
	v_add3_u32 v7, v149, v8, s14
	v_add3_u32 v99, v134, v99, s14
	v_add3_u32 v115, v139, v115, s14
	v_add3_u32 v10, v148, v9, s14
	v_add3_u32 v13, v135, v12, s14
	v_add3_u32 v12, v138, v150, s14
	v_and_b32_e32 v8, 0xffff0000, v6
	v_and_b32_e32 v9, 0xffff0000, v7
	v_and_b32_e32 v6, 0xffff0000, v99
	v_and_b32_e32 v7, 0xffff0000, v115
	v_or_b32_sdwa v151, v9, v11 dst_sel:DWORD dst_unused:UNUSED_PAD src0_sel:DWORD src1_sel:WORD_1
	v_or_b32_sdwa v150, v10, v8 dst_sel:DWORD dst_unused:UNUSED_PAD src0_sel:WORD_1 src1_sel:DWORD
	v_or_b32_sdwa v153, v7, v13 dst_sel:DWORD dst_unused:UNUSED_PAD src0_sel:DWORD src1_sel:WORD_1
	v_or_b32_sdwa v152, v12, v6 dst_sel:DWORD dst_unused:UNUSED_PAD src0_sel:WORD_1 src1_sel:DWORD
	global_store_dwordx4 v[62:63], v[150:153], off offset:2048
	global_load_dwordx4 v[156:159], v[40:41], off offset:16
	s_nop 0
	global_load_dwordx4 v[152:155], v[40:41], off
	v_add_f32_e32 v99, v218, v220
	v_add_f32_e32 v99, v221, v99
	v_add_f32_e32 v99, v219, v99
	v_add_f32_e32 v99, v222, v99
	v_add_f32_e32 v99, v224, v99
	v_add_f32_e32 v99, v225, v99
	v_pk_mul_f32 v[150:151], v[104:105], v[104:105]
	v_add_f32_e32 v99, v223, v99
	v_pk_mul_f32 v[170:171], v[100:101], v[100:101]
	v_add_f32_e32 v99, v150, v99
	v_add_f32_e32 v99, v170, v99
	v_add_f32_e32 v99, v171, v99
	v_pk_mul_f32 v[172:173], v[106:107], v[106:107]
	v_add_f32_e32 v99, v151, v99
	v_pk_mul_f32 v[174:175], v[102:103], v[102:103]
	v_add_f32_e32 v99, v172, v99
	v_add_f32_e32 v99, v174, v99
	v_add_f32_e32 v99, v175, v99
	v_add_f32_e32 v99, v173, v99
	v_pk_mul_f32 v[150:151], v[112:113], v[112:113]
	v_pk_mul_f32 v[170:171], v[108:109], v[108:109]
	v_add_f32_e32 v99, v150, v99
	v_add_f32_e32 v99, v170, v99
	v_add_f32_e32 v99, v171, v99
	v_pk_mul_f32 v[172:173], v[116:117], v[116:117]
	v_add_f32_e32 v99, v151, v99
	v_pk_mul_f32 v[174:175], v[110:111], v[110:111]
	v_add_f32_e32 v99, v172, v99
	v_add_f32_e32 v99, v174, v99
	v_add_f32_e32 v99, v175, v99
	v_add_f32_e32 v99, v173, v99
	v_pk_mul_f32 v[150:151], v[122:123], v[122:123]
	v_pk_mul_f32 v[170:171], v[118:119], v[118:119]
	v_add_f32_e32 v99, v150, v99
	v_add_f32_e32 v99, v170, v99
	v_add_f32_e32 v99, v171, v99
	v_pk_mul_f32 v[172:173], v[124:125], v[124:125]
	v_add_f32_e32 v99, v151, v99
	v_pk_mul_f32 v[174:175], v[120:121], v[120:121]
	v_add_f32_e32 v99, v172, v99
	v_add_f32_e32 v99, v174, v99
	v_add_f32_e32 v99, v175, v99
	v_add_f32_e32 v99, v173, v99
	v_pk_mul_f32 v[150:151], v[132:133], v[132:133]
	v_pk_mul_f32 v[170:171], v[128:129], v[128:129]
	v_add_f32_e32 v99, v150, v99
	v_add_f32_e32 v99, v170, v99
	v_add_f32_e32 v99, v171, v99
	v_pk_mul_f32 v[172:173], v[130:131], v[130:131]
	v_add_f32_e32 v99, v151, v99
	v_pk_mul_f32 v[174:175], v[126:127], v[126:127]
	v_add_f32_e32 v99, v172, v99
	v_add_f32_e32 v99, v174, v99
	v_add_f32_e32 v99, v175, v99
	v_add_f32_e32 v99, v173, v99
	v_pk_mul_f32 v[150:151], v[146:147], v[146:147]
	v_pk_mul_f32 v[170:171], v[142:143], v[142:143]
	v_add_f32_e32 v99, v150, v99
	v_add_f32_e32 v99, v170, v99
	v_add_f32_e32 v99, v171, v99
	v_pk_mul_f32 v[172:173], v[144:145], v[144:145]
	v_add_f32_e32 v99, v151, v99
	v_pk_mul_f32 v[174:175], v[140:141], v[140:141]
	v_add_f32_e32 v99, v172, v99
	v_add_f32_e32 v99, v174, v99
	v_add_f32_e32 v99, v175, v99
	v_add_f32_e32 v99, v173, v99
	v_pk_mul_f32 v[150:151], v[148:149], v[148:149]
	v_pk_mul_f32 v[170:171], v[136:137], v[136:137]
	v_add_f32_e32 v99, v150, v99
	v_add_f32_e32 v99, v170, v99
	v_add_f32_e32 v99, v171, v99
	v_pk_mul_f32 v[172:173], v[138:139], v[138:139]
	v_add_f32_e32 v99, v151, v99
	v_pk_mul_f32 v[174:175], v[134:135], v[134:135]
	v_add_f32_e32 v99, v172, v99
	v_add_f32_e32 v99, v174, v99
	v_add_f32_e32 v99, v175, v99
	v_add_f32_e32 v99, v173, v99
	s_waitcnt vmcnt(0)
; #define GAS __attribute__((address_space(1)))
; __device__ __forceinline__ float shx(float v, int o, int lane) { return __int_as_float(__builtin_amdgcn_ds_bpermute((lane ^ o) << 2, __float_as_int(v))); }
; __device__ __forceinline__ v4u pack8(const float (&o)[8]) { v4u w; w.x = pk2(o[0], o[1]); w.y = pk2(o[2], o[3]); w.z = pk2(o[4], o[5]); w.w = pk2(o[6], o[7]); return w; }
; __device__ __forceinline__ float wave_sum(float v, int lane) {
; #pragma unroll
;     for (int o = 1; o < 64; o <<= 1) v += shx(v, o, lane);
;     return v;
; }
; template <bool XF32, bool FINAL, bool QUANT = false> ...
;     ...
;             for (int e = 0; e < 8; ++e) s2 += x[e] * x[e];
;             const v4u pw = pack8(x); *(GAS v4u*)(xbrow + c) = pw;
;             if (QUANT) { xr[j] = pw;
; #pragma unroll
;                 for (int e = 0; e < 8; ++e) am = fmaxf(am, fabsf(x[e])); } }
;         if (j & 1) asm volatile("" ::: "memory"); }
;     if (!FINAL) { const float tot = wave_sum(s2, lane); const float rsn = 1.0f / sqrtf(tot * (1.0f / DM) + EPS); if (lane == 0) *rs_out = rsn;
	v_mov_b32_e32 v150, v153
	v_mov_b32_e32 v153, v155
	v_mov_b32_e32 v151, v154
	v_pk_fma_f32 v[154:155], v[152:153], v[214:215], v[194:195]
	v_mov_b32_e32 v170, v157
	v_mov_b32_e32 v171, v158
	v_mov_b32_e32 v157, v159
	v_pk_fma_f32 v[150:151], v[150:151], v[200:201], v[184:185]
	v_pk_mul_f32 v[158:159], v[154:155], v[154:155]
	v_pk_fma_f32 v[156:157], v[156:157], v[160:161], v[198:199]
	v_pk_mul_f32 v[160:161], v[150:151], v[150:151]
	v_add_f32_e32 v99, v158, v99
	v_add_f32_e32 v99, v160, v99
	v_add_f32_e32 v99, v161, v99
	v_pk_fma_f32 v[152:153], v[170:171], v[216:217], v[196:197]
	v_pk_mul_f32 v[170:171], v[156:157], v[156:157]
	v_add_f32_e32 v99, v159, v99
	v_pk_mul_f32 v[172:173], v[152:153], v[152:153]
	v_add_f32_e32 v99, v170, v99
	v_add_f32_e32 v99, v172, v99
	v_add_f32_e32 v99, v173, v99
	v_add_f32_e32 v99, v171, v99
	ds_bpermute_b32 v115, v163, v99
	v_and_b32_sdwa v158, v151, v203 dst_sel:DWORD dst_unused:UNUSED_PAD src0_sel:WORD_1 src1_sel:DWORD
	v_and_b32_sdwa v159, v150, v203 dst_sel:DWORD dst_unused:UNUSED_PAD src0_sel:WORD_1 src1_sel:DWORD
	v_and_b32_sdwa v164, v152, v203 dst_sel:DWORD dst_unused:UNUSED_PAD src0_sel:WORD_1 src1_sel:DWORD
	v_and_b32_sdwa v172, v156, v203 dst_sel:DWORD dst_unused:UNUSED_PAD src0_sel:WORD_1 src1_sel:DWORD
	s_waitcnt lgkmcnt(0)
	v_add_f32_e32 v99, v99, v115
	ds_bpermute_b32 v115, v165, v99
	v_add3_u32 v173, v152, v164, s14
	v_add3_u32 v164, v156, v172, s14
	v_and_b32_sdwa v160, v155, v203 dst_sel:DWORD dst_unused:UNUSED_PAD src0_sel:WORD_1 src1_sel:DWORD
	v_and_b32_sdwa v161, v154, v203 dst_sel:DWORD dst_unused:UNUSED_PAD src0_sel:WORD_1 src1_sel:DWORD
	s_waitcnt lgkmcnt(0)
	v_add_f32_e32 v99, v99, v115
	ds_bpermute_b32 v170, v166, v99
	v_add3_u32 v115, v151, v158, s14
	v_add3_u32 v158, v150, v159, s14
	v_and_b32_sdwa v162, v153, v203 dst_sel:DWORD dst_unused:UNUSED_PAD src0_sel:WORD_1 src1_sel:DWORD
	v_and_b32_sdwa v171, v157, v203 dst_sel:DWORD dst_unused:UNUSED_PAD src0_sel:WORD_1 src1_sel:DWORD
	s_waitcnt lgkmcnt(0)
	v_add_f32_e32 v99, v99, v170
	ds_bpermute_b32 v159, v167, v99
	v_add3_u32 v170, v155, v160, s14
	v_add3_u32 v160, v154, v161, s14
	v_add3_u32 v161, v153, v162, s14
	v_and_b32_e32 v162, 0xffff0000, v158
	s_waitcnt lgkmcnt(0)
	v_add_f32_e32 v99, v99, v159
	ds_bpermute_b32 v174, v168, v99
	v_and_b32_e32 v158, 0xffff0000, v173
	v_add3_u32 v171, v157, v171, s14
	v_and_b32_e32 v159, 0xffff0000, v170
	v_or_b32_sdwa v170, v160, v162 dst_sel:DWORD dst_unused:UNUSED_PAD src0_sel:WORD_1 src1_sel:DWORD
	s_waitcnt lgkmcnt(0)
	v_add_f32_e32 v172, v99, v174
	ds_bpermute_b32 v174, v169, v172
	v_and_b32_e32 v99, 0xffff0000, v171
	v_or_b32_sdwa v171, v159, v115 dst_sel:DWORD dst_unused:UNUSED_PAD src0_sel:DWORD src1_sel:WORD_1
	s_waitcnt lgkmcnt(0)
	v_add_f32_e32 v172, v172, v174
	v_fmamk_f32 v172, v172, 0x39800000, v204
	v_mul_f32_e32 v173, 0x4f800000, v172
	v_cmp_gt_f32_e32 vcc, s73, v172
	s_nop 1
	v_cndmask_b32_e32 v174, v172, v173, vcc
	v_sqrt_f32_e32 v175, v174
	v_or_b32_sdwa v173, v99, v161 dst_sel:DWORD dst_unused:UNUSED_PAD src0_sel:DWORD src1_sel:WORD_1
	v_or_b32_sdwa v172, v164, v158 dst_sel:DWORD dst_unused:UNUSED_PAD src0_sel:WORD_1 src1_sel:DWORD
	global_store_dwordx4 v[62:63], v[170:173], off offset:3072
	v_add_u32_e32 v62, -1, v175
	v_add_u32_e32 v63, 1, v175
	v_fma_f32 v170, -v62, v175, v174
	v_fma_f32 v171, -v63, v175, v174
	v_cmp_ge_f32_e64 s[42:43], 0, v170
	s_nop 1
	v_cndmask_b32_e64 v62, v175, v62, s[42:43]
	v_cmp_lt_f32_e64 s[42:43], 0, v171
	s_nop 1
	v_cndmask_b32_e64 v62, v62, v63, s[42:43]
	v_mul_f32_e32 v63, 0x37800000, v62
	v_cndmask_b32_e32 v62, v62, v63, vcc
	v_cmp_class_f32_e32 vcc, v174, v205
	s_nop 1
	v_cndmask_b32_e32 v62, v62, v174, vcc
	v_div_scale_f32 v63, s[12:13], v62, v62, 1.0
	v_rcp_f32_e32 v170, v63
	v_div_scale_f32 v171, vcc, 1.0, v62, 1.0
	v_fma_f32 v172, -v63, v170, 1.0
	v_fmac_f32_e32 v170, v172, v170
	v_mul_f32_e32 v172, v171, v170
	v_fma_f32 v173, -v63, v172, v171
	v_fmac_f32_e32 v172, v173, v170
	v_fma_f32 v63, -v63, v172, v171
	v_div_fmas_f32 v63, v63, v170, v172
	v_div_fixup_f32 v170, v63, v62, 1.0
	s_and_saveexec_b64 s[12:13], s[40:41]
	s_cbranch_execz .LBB0_944
	v_mov_b32_e32 v62, 0x120000
	global_store_dword v62, v170, s[8:9]
